# G5 epilogue column remap + half-row exchange (8x128B stores); G6 epilogue f32 loads/stores cover 8 rows x 128B via DPP half swap
# speedup vs baseline: 1.0211x; 1.0054x over previous
; #define PG8_STAGE(bufoff, gbase, voff) do { _Pragma("unroll") for (int _i = 0; _i < 2; ++_i) \
;         __builtin_amdgcn_global_load_lds((const unsigned*)((const char*)(gbase) + (voff)[_i]), (PG8_LAS unsigned*)(lds + (bufoff) + ldsw + _i * 8192), 16, 0, 0); } while (0)
; #define PG8_WAIT_V(n) asm volatile("s_waitcnt vmcnt(" #n ")" ::: "memory")
; #define PG8_BAR __builtin_amdgcn_s_barrier()
; template <class Epi, class Sched, bool ALIGN_EPI = false, bool SP2 = false>
; __device__ __forceinline__ void gemm_phase(PG8_LAS unsigned char* lds, const Gemm g, const Sched& S, const Epi& E) {
;     ...
;     for (int i = 0; i < 2; ++i) { int R, C; stage_rc(tid * 16 + i * 8192, R, C); const int Rb = Epi::PERM ? ((R & ~31) + perm32(R & 31)) : R;
;         voffA[i] = (unsigned)(R * K + C) * 2u; voffB[i] = (unsigned)(Rb * K + C) * 2u; }
;     const size_t kstep = (size_t)(BK * 2);
;     const size_t hstep = (size_t)HALF * K * 2;
;     const size_t tstep = 2 * hstep;
;     const unsigned ldsw = (unsigned)wid * 1024u;
;     const int aoff = lds_byte(wr * 64 + fr, fq * 8), boff = lds_byte(wc * 32 + fr, fq * 8);
;     ...
;     Unit cur, nxt; int ui = 0;
;     if (!S.next(0, cur)) return;
;     f32x4 acc[2][2][4][2];
; #pragma unroll
;     for (int a = 0; a < 2; ++a)
; #pragma unroll
;         for (int b = 0; b < 2; ++b)
; #pragma unroll
;             for (int m = 0; m < 4; ++m)
; #pragma unroll
;                 for (int n = 0; n < 2; ++n) acc[a][b][m][n] = (f32x4){0.f, 0.f, 0.f, 0.f};
;     bf16x8 At[4][2], B0[2][2], B1[2][2];
;     const char* cA = (const char*)g.A + (size_t)cur.pm * tstep; const char* cB = (const char*)g.Bt + (size_t)cur.pn * tstep;
;     S.a_ready(cur);
;     if constexpr (SP2) {
;         PG8_STAGE(PG8_SB(0, 0), cB, voffB); PG8_STAGE(PG8_SB(0, 1), cB + hstep, voffB); PG8_STAGE(PG8_SA(0, 0), cA, voffA); PG8_STAGE(PG8_SA(0, 1), cA + hstep, voffA);
;         if (wr == 1) PG8_BAR;
;         PG8_WAIT_V(2); PG8_BAR;
;         PG8_STAGE(PG8_SB(1, 0), cB + kstep, voffB); PG8_STAGE(PG8_SA(1, 0), cA + kstep, voffA); PG8_STAGE(PG8_SB(1, 1), cB + hstep + kstep, voffB);
;         PG8_WAIT_V(6); PG8_BAR;
.LBB0_726:
	s_or_b64 exec, exec, s[2:3]
	v_readlane_b32 s2, v252, 31
	v_mov_b32_e32 v8, v188
	v_readlane_b32 s3, v252, 32
	s_waitcnt lgkmcnt(0)
	s_barrier
	s_and_b64 vcc, exec, s[2:3]
	v_readfirstlane_b32 s4, v8
	s_cbranch_vccz .LBB0_746
	v_lshlrev_b32_e32 v0, 4, v8
	v_add_u32_e32 v3, 0x2000, v0
	v_ashrrev_i32_e32 v2, 31, v3
	v_lshrrev_b32_e32 v2, 22, v2
	v_add_u32_e32 v2, v3, v2
	v_ashrrev_i32_e32 v2, 10, v2
	v_mul_i32_i24_e32 v4, 0x400, v2
	v_sub_u32_e32 v3, v3, v4
	v_lshrrev_b32_e32 v4, 4, v3
	v_bitop3_b32 v4, v4, v3, 32 bitop3:0x6c
	v_ashrrev_i32_e32 v3, 31, v4
	v_lshrrev_b32_e32 v3, 26, v3
	v_add_u32_e32 v5, v4, v3
	v_lshlrev_b32_e32 v6, 3, v2
	v_ashrrev_i32_e32 v3, 6, v5
	v_and_b32_e32 v6, -16, v6
	v_add_u32_e32 v6, v3, v6
	v_and_b32_e32 v7, 3, v3
	s_mov_b32 s2, 0x1fffe0
	v_lshrrev_b32_e32 v9, 2, v6
	v_lshlrev_b32_e32 v10, 1, v6
	v_and_b32_e32 v5, 0xc0, v5
	v_and_or_b32 v7, v6, s2, v7
	v_and_b32_e32 v9, 4, v9
	v_and_b32_e32 v10, 24, v10
	v_sub_u32_e32 v4, v4, v5
	v_or3_b32 v7, v7, v9, v10
	v_lshlrev_b32_e32 v9, 5, v2
	v_ashrrev_i16_sdwa v4, v189, sext(v4) dst_sel:DWORD dst_unused:UNUSED_PAD src0_sel:DWORD src1_sel:BYTE_0
	v_and_b32_e32 v9, 32, v9
	v_bfe_i32 v4, v4, 0, 16
	v_add_lshl_u32 v5, v9, v4, 1
	v_lshl_add_u32 v146, v7, 11, v5
	v_lshl_add_u32 v148, v6, 11, v5
	v_bfe_i32 v5, v8, 27, 1
	v_lshrrev_b32_e32 v5, 22, v5
	v_add_u32_e32 v5, v0, v5
	v_and_b32_e32 v5, 0xfffffc00, v5
	v_sub_u32_e32 v0, v0, v5
	v_lshrrev_b32_e32 v5, 4, v0
	v_ashrrev_i32_e32 v6, 31, v8
	v_bitop3_b32 v0, v5, v0, 32 bitop3:0x6c
	v_lshrrev_b32_e32 v6, 26, v6
	v_ashrrev_i32_e32 v5, 31, v0
	v_add_u32_e32 v6, v8, v6
	v_lshrrev_b32_e32 v5, 26, v5
	v_ashrrev_i32_e32 v6, 6, v6
	v_add_u32_e32 v7, v0, v5
	v_lshlrev_b32_e32 v9, 3, v6
	v_ashrrev_i32_e32 v5, 6, v7
	v_and_b32_e32 v9, -16, v9
	v_add_u32_e32 v9, v5, v9
	v_and_b32_e32 v10, 3, v5
	v_lshrrev_b32_e32 v11, 2, v9
	v_lshlrev_b32_e32 v12, 1, v9
	v_and_b32_e32 v7, 0xc0, v7
	v_and_or_b32 v10, v9, s2, v10
	v_and_b32_e32 v11, 4, v11
	v_and_b32_e32 v12, 24, v12
	v_sub_u32_e32 v0, v0, v7
	s_ashr_i32 s5, s4, 6
	v_or3_b32 v10, v10, v11, v12
	v_lshlrev_b32_e32 v11, 5, v6
	v_ashrrev_i16_sdwa v0, v189, sext(v0) dst_sel:DWORD dst_unused:UNUSED_PAD src0_sel:DWORD src1_sel:BYTE_0
	s_lshl_b32 s28, s5, 10
	v_and_b32_e32 v11, 32, v11
	v_bfe_i32 v7, v0, 0, 16
	v_add_lshl_u32 v11, v11, v7, 1
	s_add_i32 s29, s28, 0
	v_readlane_b32 s2, v253, 6
	v_lshl_add_u32 v0, v10, 11, v11
	s_add_i32 m0, s29, 0x10000
	v_readlane_b32 s3, v253, 7
	s_ashr_i32 s14, s4, 8
	s_lshl_b32 s98, s14, 16
	v_add_u32_e32 v0, s98, v0
	s_add_i32 s99, s98, 0x20000
	v_add_u32_e32 v146, s99, v146
	v_lshl_add_u32 v150, v9, 11, v11
	s_nop 2
	global_load_lds_dwordx4 v0, s[2:3]
	s_add_i32 m0, s29, 0x12000
	s_nop 0
	global_load_lds_dwordx4 v146, s[2:3]
	v_readlane_b32 s2, v253, 4
	s_add_i32 m0, s29, 0x14000
	v_readlane_b32 s3, v253, 5
	s_nop 4
	s_sub_u32 s2, s2, 0x30000
	s_subb_u32 s3, s3, 0
	s_nop 0
	global_load_lds_dwordx4 v0, s[2:3]
	s_add_i32 m0, s29, 0x16000
	s_nop 0
	global_load_lds_dwordx4 v146, s[2:3]
	v_readlane_b32 s2, v253, 2
	v_readlane_b32 s3, v253, 3
	s_add_u32 s2, s10, s2
	s_addc_u32 s3, s11, s3
	s_add_i32 s30, s29, 0x2000
	s_mov_b32 m0, s29
	s_add_u32 s6, s2, 0x40000
	global_load_lds_dwordx4 v150, s[2:3]
	s_mov_b32 m0, s30
	s_addc_u32 s7, s3, 0
	s_add_i32 s31, s29, 0x4000
	global_load_lds_dwordx4 v148, s[2:3]
	s_mov_b32 m0, s31
	s_add_i32 s33, s29, 0x6000
	global_load_lds_dwordx4 v150, s[6:7]
	s_mov_b32 m0, s33
	s_cmp_eq_u32 s14, 1
	global_load_lds_dwordx4 v148, s[6:7]
	s_cselect_b64 s[6:7], -1, 0
	s_cmp_lg_u32 s14, 1
	s_cbranch_scc1 .LBB0_729
	s_barrier
.LBB0_729:
	v_lshrrev_b32_e32 v18, 1, v8
	v_and_b32_e32 v18, 24, v18
	v_readlane_b32 s24, v253, 6
	v_and_b32_e32 v9, 15, v8
	v_lshlrev_b32_e32 v19, 1, v18
	v_lshlrev_b32_e32 v8, 2, v8
	s_lshl_b32 s5, s5, 5
	v_readlane_b32 s25, v253, 7
	v_lshl_or_b32 v180, s14, 6, v9
	v_lshl_or_b32 v9, v9, 6, v19
	s_lshl_b32 s14, s14, 13
	v_and_b32_e32 v8, 32, v8
	s_and_b32 s5, s5, 0x60
	v_lshl_add_u64 v[10:11], s[24:25], 0, v[0:1]
	v_mov_b32_e32 v147, v1
	v_bitop3_b32 v19, v9, s14, v8 bitop3:0xde
	s_lshl_b32 s14, s5, 7
	v_lshl_add_u64 v[12:13], s[24:25], 0, v[146:147]
	v_mov_b32_e32 v151, v1
	v_bitop3_b32 v181, v9, s14, v8 bitop3:0xde
	s_add_i32 m0, s29, 0x18000
	v_lshl_add_u64 v[8:9], v[10:11], 0, s[84:85]
	v_lshl_add_u64 v[14:15], s[2:3], 0, v[150:151]
	v_mov_b32_e32 v149, v1
	s_waitcnt vmcnt(2)
	s_barrier
	global_load_lds_dwordx4 v[8:9], off
	v_lshl_add_u64 v[8:9], v[12:13], 0, s[84:85]
	s_add_i32 m0, s29, 0x1a000
	s_add_i32 s34, s29, 0x8000
	v_lshl_add_u64 v[16:17], s[2:3], 0, v[148:149]
	global_load_lds_dwordx4 v[8:9], off
	v_lshl_add_u64 v[8:9], v[14:15], 0, s[84:85]
	s_mov_b32 m0, s34
	s_add_i32 s35, s29, 0xa000
	v_readlane_b32 s14, v253, 8
	global_load_lds_dwordx4 v[8:9], off
	v_lshl_add_u64 v[8:9], v[16:17], 0, s[84:85]
	s_mov_b32 m0, s35
	v_readlane_b32 s15, v253, 9
	global_load_lds_dwordx4 v[8:9], off
	s_add_i32 m0, s29, 0x1c000
	s_sub_u32 s14, s14, 0x30000
	s_subb_u32 s15, s15, 0
	v_lshl_add_u64 v[8:9], s[14:15], 0, v[0:1]
	global_load_lds_dwordx4 v[8:9], off
	v_lshl_add_u64 v[8:9], s[14:15], 0, v[146:147]
	s_add_i32 m0, s29, 0x1e000
	s_cmpk_lt_u32 s4, 0x100
	global_load_lds_dwordx4 v[8:9], off
	v_lshlrev_b32_e32 v8, 14, v6
	v_and_b32_e32 v8, 0xffff8000, v8
	v_lshl_add_u32 v5, v5, 11, v8
	v_and_b32_e32 v6, 1, v6
	v_lshl_or_b32 v5, v6, 6, v5
	v_lshl_add_u32 v152, v7, 1, v5
	v_lshlrev_b32_e32 v5, 14, v2
	v_and_b32_e32 v5, 0xffff8000, v5
	s_waitcnt vmcnt(6)
	v_lshl_add_u32 v3, v3, 11, v5
	v_and_b32_e32 v2, 1, v2
	v_or_b32_e32 v182, s5, v18
	v_lshl_or_b32 v2, v2, 6, v3
	v_readlane_b32 s4, v253, 0
	s_cselect_b64 s[14:15], -1, 0
	v_mov_b32_e32 v153, v1
	v_lshl_add_u32 v154, v4, 1, v2
	v_mov_b32_e32 v155, v1
	s_mov_b32 s36, 0
	v_add_u32_e32 v183, 0, v19
	v_readlane_b32 s37, v252, 63
	s_mov_b32 s38, s4
	s_barrier
	v_readlane_b32 s5, v253, 1
	s_branch .LBB0_732

; #define PG8_STAGE(bufoff, gbase, voff) do { _Pragma("unroll") for (int _i = 0; _i < 2; ++_i) \
;         __builtin_amdgcn_global_load_lds((const unsigned*)((const char*)(gbase) + (voff)[_i]), (PG8_LAS unsigned*)(lds + (bufoff) + ldsw + _i * 8192), 16, 0, 0); } while (0)
; #define PG8_LDA(dst, b, h) do { _Pragma("unroll") for (int m = 0; m < 4; ++m) _Pragma("unroll") for (int k = 0; k < 2; ++k) dst[m][k] = *(const PG8_LAS bf16x8*)(lds + PG8_SA(b, h) + aoff + m * 2048 + k * 1024); } while (0)
; #define PG8_LDB(dst, b, h) do { _Pragma("unroll") for (int n = 0; n < 2; ++n) _Pragma("unroll") for (int k = 0; k < 2; ++k) dst[n][k] = *(const PG8_LAS bf16x8*)(lds + PG8_SB(b, h) + boff + n * 2048 + k * 1024); } while (0)
; #define PG8_MMA(ai, bj, At, Bt) do { __builtin_amdgcn_s_setprio(1); _Pragma("unroll") for (int m = 0; m < 4; ++m) _Pragma("unroll") for (int n = 0; n < 2; ++n) _Pragma("unroll") for (int k = 0; k < 2; ++k) \
;         acc[ai][bj][m][n] = __builtin_amdgcn_mfma_f32_16x16x32_bf16(Bt[n][k], At[m][k], acc[ai][bj][m][n], 0, 0, 0); __builtin_amdgcn_s_setprio(0); } while (0)
; #define PG8_WAIT_V(n) asm volatile("s_waitcnt vmcnt(" #n ")" ::: "memory")
; template <class Epi, class Sched, bool ALIGN_EPI = false, bool SP2 = false>
; __device__ __forceinline__ void gemm_phase(PG8_LAS unsigned char* lds, const Gemm g, const Sched& S, const Epi& E) {
;     ...
;             PG8_LDB(B0, 0, 0); PG8_LDB(B1, 0, 1); PG8_SCHED; PG8_LDA(At, 0, 0); PG8_STAGE(PG8_SA(1, 1), a1 + hstep, voffA);
;             PG8_WAIT_V(8); PG8_WAIT_L(0); PG8_BAR; PG8_MMA(0, 0, At, B0); PG8_MMA(0, 1, At, B1); PG8_BAR; PG8_SCHED;
;             PG8_LDA(At, 0, 1); PG8_STAGE(PG8_SB(0, 0), b2, voffB); PG8_STAGE(PG8_SB(0, 1), b2 + hstep, voffB); PG8_STAGE(PG8_SA(0, 0), a2, voffA);
;             PG8_WAIT_V(8); PG8_WAIT_L(0); PG8_BAR; PG8_MMA(1, 0, At, B0); PG8_MMA(1, 1, At, B1); PG8_BAR; PG8_SCHED;
;             PG8_LDB(B0, 1, 0); PG8_LDB(B1, 1, 1); PG8_SCHED; PG8_LDA(At, 1, 0); PG8_STAGE(PG8_SA(0, 1), a2 + hstep, voffA);
;             PG8_WAIT_V(8); PG8_WAIT_L(0); PG8_BAR; PG8_MMA(0, 0, At, B0); PG8_MMA(0, 1, At, B1); PG8_BAR; PG8_SCHED;
;             PG8_LDA(At, 1, 1); PG8_STAGE(PG8_SB(1, 0), b3, voffB); PG8_STAGE(PG8_SB(1, 1), b3 + hstep, voffB); PG8_STAGE(PG8_SA(1, 0), a3, voffA);
;             PG8_WAIT_V(8); PG8_WAIT_L(0); PG8_BAR; PG8_MMA(1, 0, At, B0); PG8_MMA(1, 1, At, B1); PG8_BAR; PG8_SCHED;
.LBB0_739:
	s_add_u32 s24, s2, 0xfffc0080
	s_addc_u32 s25, s3, -1
	s_add_i32 s44, 0, 0x10000
	s_cmp_eq_u32 s43, 12
	s_cselect_b32 s27, s19, s25
	s_cselect_b32 s26, s39, s24
	s_cselect_b32 s25, s17, s42
	s_cselect_b32 s24, s40, s41
	s_add_i32 s46, 0, 0x14000
	v_add_u32_e32 v62, s44, v181
	v_add_u32_e32 v160, s46, v181
	ds_read_b128 v[42:45], v62
	ds_read_b128 v[46:49], v62 offset:1024
	ds_read_b128 v[58:61], v62 offset:2048
	ds_read_b128 v[62:65], v62 offset:3072
	ds_read_b128 v[156:159], v160
	ds_read_b128 v[184:187], v160 offset:1024
	ds_read_b128 v[200:203], v160 offset:2048
	ds_read_b128 v[204:207], v160 offset:3072
	v_lshl_add_u64 v[160:161], s[2:3], 0, v[152:153]
	s_add_i32 m0, s29, 0xc000
	ds_read_b128 v[208:211], v183
	ds_read_b128 v[212:215], v183 offset:1024
	ds_read_b128 v[216:219], v183 offset:2048
	ds_read_b128 v[220:223], v183 offset:3072
	ds_read_b128 v[224:227], v183 offset:4096
	ds_read_b128 v[228:231], v183 offset:5120
	ds_read_b128 v[232:235], v183 offset:6144
	ds_read_b128 v[236:239], v183 offset:7168
	global_load_lds_dwordx4 v[160:161], off
	v_lshl_add_u64 v[160:161], s[2:3], 0, v[154:155]
	s_add_i32 m0, s29, 0xe000
	s_nop 0
	global_load_lds_dwordx4 v[160:161], off
	s_waitcnt vmcnt(8)
	s_waitcnt lgkmcnt(0)
	s_barrier
	s_setprio 1
	s_waitcnt lgkmcnt(0)
	v_mfma_f32_16x16x32_bf16 v[142:145], v[42:45], v[208:211], v[142:145]
	v_mfma_f32_16x16x32_bf16 v[138:141], v[58:61], v[208:211], v[138:141]
	v_mfma_f32_16x16x32_bf16 v[126:129], v[42:45], v[216:219], v[126:129]
	v_mfma_f32_16x16x32_bf16 v[122:125], v[58:61], v[216:219], v[122:125]
	v_mfma_f32_16x16x32_bf16 v[110:113], v[42:45], v[224:227], v[110:113]
	v_mfma_f32_16x16x32_bf16 v[106:109], v[58:61], v[224:227], v[106:109]
	v_mfma_f32_16x16x32_bf16 v[94:97], v[42:45], v[232:235], v[94:97]
	v_mfma_f32_16x16x32_bf16 v[90:93], v[58:61], v[232:235], v[90:93]
	v_mfma_f32_16x16x32_bf16 v[142:145], v[46:49], v[212:215], v[142:145]
	v_mfma_f32_16x16x32_bf16 v[138:141], v[62:65], v[212:215], v[138:141]
	v_mfma_f32_16x16x32_bf16 v[126:129], v[46:49], v[220:223], v[126:129]
	v_mfma_f32_16x16x32_bf16 v[122:125], v[62:65], v[220:223], v[122:125]
	v_mfma_f32_16x16x32_bf16 v[110:113], v[46:49], v[228:231], v[110:113]
	v_mfma_f32_16x16x32_bf16 v[106:109], v[62:65], v[228:231], v[106:109]
	v_mfma_f32_16x16x32_bf16 v[94:97], v[46:49], v[236:239], v[94:97]
	v_mfma_f32_16x16x32_bf16 v[90:93], v[62:65], v[236:239], v[90:93]
	s_setprio 0
	s_setprio 1
	v_mfma_f32_16x16x32_bf16 v[134:137], v[156:159], v[208:211], v[134:137]
	v_mfma_f32_16x16x32_bf16 v[130:133], v[200:203], v[208:211], v[130:133]
	v_mfma_f32_16x16x32_bf16 v[118:121], v[156:159], v[216:219], v[118:121]
	v_mfma_f32_16x16x32_bf16 v[114:117], v[200:203], v[216:219], v[114:117]
	v_mfma_f32_16x16x32_bf16 v[102:105], v[156:159], v[224:227], v[102:105]
	v_mfma_f32_16x16x32_bf16 v[98:101], v[200:203], v[224:227], v[98:101]
	v_mfma_f32_16x16x32_bf16 v[86:89], v[156:159], v[232:235], v[86:89]
	v_mfma_f32_16x16x32_bf16 v[82:85], v[200:203], v[232:235], v[82:85]
	v_mfma_f32_16x16x32_bf16 v[134:137], v[184:187], v[212:215], v[134:137]
	v_mfma_f32_16x16x32_bf16 v[130:133], v[204:207], v[212:215], v[130:133]
	v_mfma_f32_16x16x32_bf16 v[118:121], v[184:187], v[220:223], v[118:121]
	v_mfma_f32_16x16x32_bf16 v[114:117], v[204:207], v[220:223], v[114:117]
	v_mfma_f32_16x16x32_bf16 v[102:105], v[184:187], v[228:231], v[102:105]
	v_mfma_f32_16x16x32_bf16 v[98:101], v[204:207], v[228:231], v[98:101]
	v_mfma_f32_16x16x32_bf16 v[86:89], v[184:187], v[236:239], v[86:89]
	v_mfma_f32_16x16x32_bf16 v[82:85], v[204:207], v[236:239], v[82:85]
	s_setprio 0
	s_barrier
	s_add_i32 s44, s44, s28
	v_lshl_add_u64 v[160:161], s[24:25], 0, v[0:1]
	s_mov_b32 m0, s44
	ds_read_b128 v[208:211], v183 offset:16384
	ds_read_b128 v[212:215], v183 offset:17408
	ds_read_b128 v[216:219], v183 offset:18432
	ds_read_b128 v[220:223], v183 offset:19456
	ds_read_b128 v[224:227], v183 offset:20480
	ds_read_b128 v[228:231], v183 offset:21504
	ds_read_b128 v[232:235], v183 offset:22528
	ds_read_b128 v[236:239], v183 offset:23552
	global_load_lds_dwordx4 v[160:161], off
	s_add_i32 m0, s44, 0x2000
	s_add_u32 s44, s24, 0x10000
	v_lshl_add_u64 v[162:163], s[24:25], 0, v[146:147]
	s_addc_u32 s45, s25, 0
	s_add_i32 s46, s46, s28
	global_load_lds_dwordx4 v[162:163], off
	v_lshl_add_u64 v[164:165], s[44:45], 0, v[0:1]
	s_mov_b32 m0, s46
	v_lshl_add_u64 v[178:179], s[26:27], 0, v[148:149]
	global_load_lds_dwordx4 v[164:165], off
	v_lshl_add_u64 v[164:165], s[44:45], 0, v[146:147]
	s_add_i32 m0, s46, 0x2000
	s_nop 0
	global_load_lds_dwordx4 v[164:165], off
	v_lshl_add_u64 v[164:165], s[26:27], 0, v[150:151]
	s_mov_b32 m0, s29
	s_nop 0
	global_load_lds_dwordx4 v[164:165], off
	s_mov_b32 m0, s30
	s_nop 0
	global_load_lds_dwordx4 v[178:179], off
	s_waitcnt vmcnt(8)
	s_waitcnt lgkmcnt(0)
	s_barrier
; #define PG8_STAGE(bufoff, gbase, voff) do { _Pragma("unroll") for (int _i = 0; _i < 2; ++_i) \
;         __builtin_amdgcn_global_load_lds((const unsigned*)((const char*)(gbase) + (voff)[_i]), (PG8_LAS unsigned*)(lds + (bufoff) + ldsw + _i * 8192), 16, 0, 0); } while (0)
; #define PG8_LDA(dst, b, h) do { _Pragma("unroll") for (int m = 0; m < 4; ++m) _Pragma("unroll") for (int k = 0; k < 2; ++k) dst[m][k] = *(const PG8_LAS bf16x8*)(lds + PG8_SA(b, h) + aoff + m * 2048 + k * 1024); } while (0)
; #define PG8_LDB(dst, b, h) do { _Pragma("unroll") for (int n = 0; n < 2; ++n) _Pragma("unroll") for (int k = 0; k < 2; ++k) dst[n][k] = *(const PG8_LAS bf16x8*)(lds + PG8_SB(b, h) + boff + n * 2048 + k * 1024); } while (0)
; #define PG8_MMA(ai, bj, At, Bt) do { __builtin_amdgcn_s_setprio(1); _Pragma("unroll") for (int m = 0; m < 4; ++m) _Pragma("unroll") for (int n = 0; n < 2; ++n) _Pragma("unroll") for (int k = 0; k < 2; ++k) \
;         acc[ai][bj][m][n] = __builtin_amdgcn_mfma_f32_16x16x32_bf16(Bt[n][k], At[m][k], acc[ai][bj][m][n], 0, 0, 0); __builtin_amdgcn_s_setprio(0); } while (0)
; #define PG8_WAIT_V(n) asm volatile("s_waitcnt vmcnt(" #n ")" ::: "memory")
; #define PG8_WAIT_L(n) asm volatile("s_waitcnt lgkmcnt(" #n ")" ::: "memory")
; #define PG8_BAR __builtin_amdgcn_s_barrier()
; #define PG8_SCHED __builtin_amdgcn_sched_barrier(0)
; template <class Epi, class Sched, bool ALIGN_EPI = false, bool SP2 = false>
; __device__ __forceinline__ void gemm_phase(PG8_LAS unsigned char* lds, const Gemm g, const Sched& S, const Epi& E) {
;     ...
;             PG8_WAIT_V(8); PG8_WAIT_L(0); PG8_BAR; PG8_MMA(1, 0, At, B0); PG8_MMA(1, 1, At, B1); PG8_BAR; PG8_SCHED;
;             PG8_LDB(B0, 1, 0); PG8_LDB(B1, 1, 1); PG8_SCHED; PG8_LDA(At, 1, 0); PG8_STAGE(PG8_SA(0, 1), a2 + hstep, voffA);
;             PG8_WAIT_V(8); PG8_WAIT_L(0); PG8_BAR; PG8_MMA(0, 0, At, B0); PG8_MMA(0, 1, At, B1); PG8_BAR; PG8_SCHED;
;             PG8_LDA(At, 1, 1); PG8_STAGE(PG8_SB(1, 0), b3, voffB); PG8_STAGE(PG8_SB(1, 1), b3 + hstep, voffB); PG8_STAGE(PG8_SA(1, 0), a3, voffA);
	s_setprio 1
	s_waitcnt lgkmcnt(0)
	v_mfma_f32_16x16x32_bf16 v[78:81], v[42:45], v[208:211], v[78:81]
	v_mfma_f32_16x16x32_bf16 v[74:77], v[58:61], v[208:211], v[74:77]
	v_mfma_f32_16x16x32_bf16 v[54:57], v[42:45], v[216:219], v[54:57]
	v_mfma_f32_16x16x32_bf16 v[50:53], v[58:61], v[216:219], v[50:53]
	v_mfma_f32_16x16x32_bf16 v[30:33], v[42:45], v[224:227], v[30:33]
	v_mfma_f32_16x16x32_bf16 v[26:29], v[58:61], v[224:227], v[26:29]
	v_mfma_f32_16x16x32_bf16 v[14:17], v[42:45], v[232:235], v[14:17]
	v_mfma_f32_16x16x32_bf16 v[10:13], v[58:61], v[232:235], v[10:13]
	v_mfma_f32_16x16x32_bf16 v[78:81], v[46:49], v[212:215], v[78:81]
	v_mfma_f32_16x16x32_bf16 v[74:77], v[62:65], v[212:215], v[74:77]
	v_mfma_f32_16x16x32_bf16 v[54:57], v[46:49], v[220:223], v[54:57]
	v_mfma_f32_16x16x32_bf16 v[50:53], v[62:65], v[220:223], v[50:53]
	v_mfma_f32_16x16x32_bf16 v[30:33], v[46:49], v[228:231], v[30:33]
	v_mfma_f32_16x16x32_bf16 v[26:29], v[62:65], v[228:231], v[26:29]
	v_mfma_f32_16x16x32_bf16 v[14:17], v[46:49], v[236:239], v[14:17]
	v_mfma_f32_16x16x32_bf16 v[10:13], v[62:65], v[236:239], v[10:13]
	s_setprio 0
	s_setprio 1
	v_mfma_f32_16x16x32_bf16 v[38:41], v[156:159], v[216:219], v[38:41]
	v_mfma_f32_16x16x32_bf16 v[34:37], v[200:203], v[216:219], v[34:37]
	v_mfma_f32_16x16x32_bf16 v[22:25], v[156:159], v[224:227], v[22:25]
	v_mfma_f32_16x16x32_bf16 v[18:21], v[200:203], v[224:227], v[18:21]
	v_mfma_f32_16x16x32_bf16 v[6:9], v[156:159], v[232:235], v[6:9]
	v_mfma_f32_16x16x32_bf16 v[2:5], v[200:203], v[232:235], v[2:5]
	v_mfma_f32_16x16x32_bf16 v[42:45], v[156:159], v[208:211], v[70:73]
	v_mfma_f32_16x16x32_bf16 v[46:49], v[200:203], v[208:211], v[66:69]
	v_mfma_f32_16x16x32_bf16 v[38:41], v[184:187], v[220:223], v[38:41]
	v_mfma_f32_16x16x32_bf16 v[34:37], v[204:207], v[220:223], v[34:37]
	v_mfma_f32_16x16x32_bf16 v[22:25], v[184:187], v[228:231], v[22:25]
	v_mfma_f32_16x16x32_bf16 v[18:21], v[204:207], v[228:231], v[18:21]
	v_mfma_f32_16x16x32_bf16 v[6:9], v[184:187], v[236:239], v[6:9]
	v_mfma_f32_16x16x32_bf16 v[2:5], v[204:207], v[236:239], v[2:5]
	v_mfma_f32_16x16x32_bf16 v[42:45], v[184:187], v[212:215], v[42:45]
	v_mfma_f32_16x16x32_bf16 v[46:49], v[204:207], v[212:215], v[46:49]
	s_setprio 0
	s_barrier
	s_add_i32 s44, 0, 0x18000
	s_add_i32 s45, 0, 0x1c000
	v_add_u32_e32 v70, s44, v181
	v_add_u32_e32 v190, s45, v181
	ds_read_b128 v[58:61], v70
	ds_read_b128 v[62:65], v70 offset:1024
	ds_read_b128 v[66:69], v70 offset:2048
	ds_read_b128 v[70:73], v70 offset:3072
	ds_read_b128 v[156:159], v190
	ds_read_b128 v[184:187], v190 offset:1024
	ds_read_b128 v[200:203], v190 offset:2048
	ds_read_b128 v[204:207], v190 offset:3072
	s_add_u32 s26, s26, 0x40000
	s_addc_u32 s27, s27, 0
	s_mov_b32 m0, s31
	v_lshl_add_u64 v[190:191], s[26:27], 0, v[150:151]
	ds_read_b128 v[208:211], v183 offset:32768
	ds_read_b128 v[212:215], v183 offset:33792
	ds_read_b128 v[216:219], v183 offset:34816
	ds_read_b128 v[220:223], v183 offset:35840
	ds_read_b128 v[224:227], v183 offset:36864
	ds_read_b128 v[228:231], v183 offset:37888
	ds_read_b128 v[232:235], v183 offset:38912
	ds_read_b128 v[236:239], v183 offset:39936
	global_load_lds_dwordx4 v[190:191], off
	v_lshl_add_u64 v[190:191], s[26:27], 0, v[148:149]
	s_mov_b32 m0, s33
	s_nop 0
	global_load_lds_dwordx4 v[190:191], off
	s_waitcnt vmcnt(8)
	s_waitcnt lgkmcnt(0)
	s_barrier
	s_setprio 1
	s_waitcnt lgkmcnt(0)
	v_mfma_f32_16x16x32_bf16 v[142:145], v[58:61], v[208:211], v[142:145]
	v_mfma_f32_16x16x32_bf16 v[138:141], v[66:69], v[208:211], v[138:141]
	v_mfma_f32_16x16x32_bf16 v[126:129], v[58:61], v[216:219], v[126:129]
	v_mfma_f32_16x16x32_bf16 v[122:125], v[66:69], v[216:219], v[122:125]
	v_mfma_f32_16x16x32_bf16 v[110:113], v[58:61], v[224:227], v[110:113]
	v_mfma_f32_16x16x32_bf16 v[106:109], v[66:69], v[224:227], v[106:109]
	v_mfma_f32_16x16x32_bf16 v[94:97], v[58:61], v[232:235], v[94:97]
	v_mfma_f32_16x16x32_bf16 v[90:93], v[66:69], v[232:235], v[90:93]
	v_mfma_f32_16x16x32_bf16 v[142:145], v[62:65], v[212:215], v[142:145]
	v_mfma_f32_16x16x32_bf16 v[138:141], v[70:73], v[212:215], v[138:141]
	v_mfma_f32_16x16x32_bf16 v[126:129], v[62:65], v[220:223], v[126:129]
	v_mfma_f32_16x16x32_bf16 v[122:125], v[70:73], v[220:223], v[122:125]
	v_mfma_f32_16x16x32_bf16 v[110:113], v[62:65], v[228:231], v[110:113]
	v_mfma_f32_16x16x32_bf16 v[106:109], v[70:73], v[228:231], v[106:109]
	v_mfma_f32_16x16x32_bf16 v[94:97], v[62:65], v[236:239], v[94:97]
	v_mfma_f32_16x16x32_bf16 v[90:93], v[70:73], v[236:239], v[90:93]
	s_setprio 0
	s_setprio 1
	v_mfma_f32_16x16x32_bf16 v[134:137], v[156:159], v[208:211], v[134:137]
	v_mfma_f32_16x16x32_bf16 v[130:133], v[200:203], v[208:211], v[130:133]
	v_mfma_f32_16x16x32_bf16 v[118:121], v[156:159], v[216:219], v[118:121]
	v_mfma_f32_16x16x32_bf16 v[114:117], v[200:203], v[216:219], v[114:117]
	v_mfma_f32_16x16x32_bf16 v[102:105], v[156:159], v[224:227], v[102:105]
	v_mfma_f32_16x16x32_bf16 v[98:101], v[200:203], v[224:227], v[98:101]
	v_mfma_f32_16x16x32_bf16 v[86:89], v[156:159], v[232:235], v[86:89]
	v_mfma_f32_16x16x32_bf16 v[82:85], v[200:203], v[232:235], v[82:85]
	v_mfma_f32_16x16x32_bf16 v[134:137], v[184:187], v[212:215], v[134:137]
	v_mfma_f32_16x16x32_bf16 v[130:133], v[204:207], v[212:215], v[130:133]
	v_mfma_f32_16x16x32_bf16 v[118:121], v[184:187], v[220:223], v[118:121]
	v_mfma_f32_16x16x32_bf16 v[114:117], v[204:207], v[220:223], v[114:117]
	v_mfma_f32_16x16x32_bf16 v[102:105], v[184:187], v[228:231], v[102:105]
	v_mfma_f32_16x16x32_bf16 v[98:101], v[204:207], v[228:231], v[98:101]
	v_mfma_f32_16x16x32_bf16 v[86:89], v[184:187], v[236:239], v[86:89]
	v_mfma_f32_16x16x32_bf16 v[82:85], v[204:207], v[236:239], v[82:85]
	s_setprio 0
	s_barrier
; #define PG8_STAGE(bufoff, gbase, voff) do { _Pragma("unroll") for (int _i = 0; _i < 2; ++_i) \
;         __builtin_amdgcn_global_load_lds((const unsigned*)((const char*)(gbase) + (voff)[_i]), (PG8_LAS unsigned*)(lds + (bufoff) + ldsw + _i * 8192), 16, 0, 0); } while (0)
; #define PG8_LDA(dst, b, h) do { _Pragma("unroll") for (int m = 0; m < 4; ++m) _Pragma("unroll") for (int k = 0; k < 2; ++k) dst[m][k] = *(const PG8_LAS bf16x8*)(lds + PG8_SA(b, h) + aoff + m * 2048 + k * 1024); } while (0)
; #define PG8_MMA(ai, bj, At, Bt) do { __builtin_amdgcn_s_setprio(1); _Pragma("unroll") for (int m = 0; m < 4; ++m) _Pragma("unroll") for (int n = 0; n < 2; ++n) _Pragma("unroll") for (int k = 0; k < 2; ++k) \
;         acc[ai][bj][m][n] = __builtin_amdgcn_mfma_f32_16x16x32_bf16(Bt[n][k], At[m][k], acc[ai][bj][m][n], 0, 0, 0); __builtin_amdgcn_s_setprio(0); } while (0)
; #define PG8_WAIT_V(n) asm volatile("s_waitcnt vmcnt(" #n ")" ::: "memory")
; #define PG8_WAIT_L(n) asm volatile("s_waitcnt lgkmcnt(" #n ")" ::: "memory")
; #define PG8_BAR __builtin_amdgcn_s_barrier()
; #define PG8_SCHED __builtin_amdgcn_sched_barrier(0)
; template <class Epi, class Sched, bool ALIGN_EPI = false, bool SP2 = false>
; __device__ __forceinline__ void gemm_phase(PG8_LAS unsigned char* lds, const Gemm g, const Sched& S, const Epi& E) {
;     ...
;             PG8_LDA(At, 1, 1); PG8_STAGE(PG8_SB(1, 0), b3, voffB); PG8_STAGE(PG8_SB(1, 1), b3 + hstep, voffB); PG8_STAGE(PG8_SA(1, 0), a3, voffA);
;             PG8_WAIT_V(8); PG8_WAIT_L(0); PG8_BAR; PG8_MMA(1, 0, At, B0); PG8_MMA(1, 1, At, B1); PG8_BAR; PG8_SCHED;
;     DI void operator()(const f32x4 (&acc)[2][2][4][2], const Unit& u, int wr, int wc, int fr, int fq) const {
;         const int row0 = u.pm * 256 + wr * 64 + fr, col0 = u.pn * 256 + wc * 32 + 8 * fq;
;         const int bb = (grow0 + u.pm * 256) >> 11;
;         f32x4 bs[2][2];
; #pragma unroll
;         for (int bj = 0; bj < 2; ++bj) { const float* bp = bias2 + (size_t)bb * 4096 + col0 + bj * 128; bs[bj][0] = *(const f32x4*)bp; bs[bj][1] = *(const f32x4*)(bp + 4); }
; #pragma unroll
;         for (int ai = 0; ai < 2; ++ai)
; #pragma unroll
;             for (int m = 0; m < 4; ++m) { bf16* rowp = O + (size_t)(row0 + ai * 128 + m * 16) * 4096 + col0;
;                 const float rstd = rsqrtf(rowss[row0 + ai * 128 + m * 16] * (1.0f / 1024.0f) + 1e-6f);
	s_add_i32 s26, s44, s28
	v_lshl_add_u64 v[160:161], v[160:161], 0, s[84:85]
	s_mov_b32 m0, s26
	ds_read_b128 v[208:211], v183 offset:49152
	ds_read_b128 v[212:215], v183 offset:50176
	ds_read_b128 v[216:219], v183 offset:51200
	ds_read_b128 v[220:223], v183 offset:52224
	ds_read_b128 v[224:227], v183 offset:53248
	ds_read_b128 v[228:231], v183 offset:54272
	ds_read_b128 v[232:235], v183 offset:55296
	ds_read_b128 v[236:239], v183 offset:56320
	global_load_lds_dwordx4 v[160:161], off
	s_add_i32 m0, s26, 0x2000
	s_add_u32 s24, s24, 0x10080
	v_lshl_add_u64 v[160:161], v[162:163], 0, s[84:85]
	s_addc_u32 s25, s25, 0
	s_add_i32 s26, s45, s28
	global_load_lds_dwordx4 v[160:161], off
	v_lshl_add_u64 v[160:161], s[24:25], 0, v[0:1]
	s_mov_b32 m0, s26
	s_nop 0
	global_load_lds_dwordx4 v[160:161], off
	v_lshl_add_u64 v[160:161], s[24:25], 0, v[146:147]
	s_add_i32 m0, s26, 0x2000
	s_nop 0
	global_load_lds_dwordx4 v[160:161], off
	v_lshl_add_u64 v[160:161], v[164:165], 0, s[84:85]
	s_mov_b32 m0, s34
	s_nop 0
	global_load_lds_dwordx4 v[160:161], off
	v_lshl_add_u64 v[160:161], v[178:179], 0, s[84:85]
	s_mov_b32 m0, s35
	s_nop 0
	global_load_lds_dwordx4 v[160:161], off
	s_waitcnt vmcnt(8)
	s_waitcnt lgkmcnt(0)
	s_barrier
	s_setprio 1
	s_waitcnt lgkmcnt(0)
	v_mfma_f32_16x16x32_bf16 v[78:81], v[58:61], v[208:211], v[78:81]
	v_mfma_f32_16x16x32_bf16 v[74:77], v[66:69], v[208:211], v[74:77]
	v_mfma_f32_16x16x32_bf16 v[54:57], v[58:61], v[216:219], v[54:57]
	v_mfma_f32_16x16x32_bf16 v[50:53], v[66:69], v[216:219], v[50:53]
	v_mfma_f32_16x16x32_bf16 v[30:33], v[58:61], v[224:227], v[30:33]
	v_mfma_f32_16x16x32_bf16 v[26:29], v[66:69], v[224:227], v[26:29]
	v_mfma_f32_16x16x32_bf16 v[14:17], v[58:61], v[232:235], v[14:17]
	v_mfma_f32_16x16x32_bf16 v[10:13], v[66:69], v[232:235], v[10:13]
	v_mfma_f32_16x16x32_bf16 v[78:81], v[62:65], v[212:215], v[78:81]
	v_mfma_f32_16x16x32_bf16 v[74:77], v[70:73], v[212:215], v[74:77]
	v_mfma_f32_16x16x32_bf16 v[54:57], v[62:65], v[220:223], v[54:57]
	v_mfma_f32_16x16x32_bf16 v[50:53], v[70:73], v[220:223], v[50:53]
	v_mfma_f32_16x16x32_bf16 v[30:33], v[62:65], v[228:231], v[30:33]
	v_mfma_f32_16x16x32_bf16 v[26:29], v[70:73], v[228:231], v[26:29]
	v_mfma_f32_16x16x32_bf16 v[14:17], v[62:65], v[236:239], v[14:17]
	v_mfma_f32_16x16x32_bf16 v[10:13], v[70:73], v[236:239], v[10:13]
	s_setprio 0
	s_setprio 1
	v_mfma_f32_16x16x32_bf16 v[42:45], v[156:159], v[208:211], v[42:45]
	v_mfma_f32_16x16x32_bf16 v[70:73], v[184:187], v[212:215], v[42:45]
	v_mfma_f32_16x16x32_bf16 v[42:45], v[200:203], v[208:211], v[46:49]
	v_mfma_f32_16x16x32_bf16 v[38:41], v[156:159], v[216:219], v[38:41]
	v_mfma_f32_16x16x32_bf16 v[34:37], v[200:203], v[216:219], v[34:37]
	v_mfma_f32_16x16x32_bf16 v[22:25], v[156:159], v[224:227], v[22:25]
	v_mfma_f32_16x16x32_bf16 v[18:21], v[200:203], v[224:227], v[18:21]
	v_mfma_f32_16x16x32_bf16 v[6:9], v[156:159], v[232:235], v[6:9]
	v_mfma_f32_16x16x32_bf16 v[2:5], v[200:203], v[232:235], v[2:5]
	v_mfma_f32_16x16x32_bf16 v[66:69], v[204:207], v[212:215], v[42:45]
	v_mfma_f32_16x16x32_bf16 v[38:41], v[184:187], v[220:223], v[38:41]
	v_mfma_f32_16x16x32_bf16 v[34:37], v[204:207], v[220:223], v[34:37]
	v_mfma_f32_16x16x32_bf16 v[22:25], v[184:187], v[228:231], v[22:25]
	v_mfma_f32_16x16x32_bf16 v[18:21], v[204:207], v[228:231], v[18:21]
	v_mfma_f32_16x16x32_bf16 v[6:9], v[184:187], v[236:239], v[6:9]
	v_mfma_f32_16x16x32_bf16 v[2:5], v[204:207], v[236:239], v[2:5]
	s_setprio 0
	s_barrier
	s_add_i32 s43, s43, 2
	s_add_u32 s2, s2, 0x100
	s_addc_u32 s3, s3, 0
	s_add_u32 s41, s41, 0x100
	s_addc_u32 s42, s42, 0
	s_cmp_gt_u32 s43, 13
	s_cbranch_scc0 .LBB0_739
	s_and_b64 vcc, exec, s[14:15]
	s_cbranch_vccz .LBB0_742
	s_barrier
.LBB0_742:
	s_lshl_b32 s17, s38, 8
	v_readlane_b32 s2, v254, 56
	s_add_i32 s2, s17, s2
	v_readlane_b32 s3, v254, 57
	s_ashr_i32 s2, s2, 11
	s_ashr_i32 s3, s2, 31
	v_add_u32_e32 v160, s17, v180
	v_lshl_or_b32 v156, s37, 8, v182
	s_lshl_b64 s[2:3], s[2:3], 14
	v_readlane_b32 s24, v251, 44
	v_ashrrev_i32_e32 v161, 31, v160
	v_readlane_b32 s25, v251, 45
	s_add_u32 s2, s24, s2
	v_ashrrev_i32_e32 v157, 31, v156
	v_lshlrev_b64 v[158:159], 13, v[160:161]
	s_addc_u32 s3, s25, s3
	v_lshl_add_u64 v[158:159], s[86:87], 0, v[158:159]
	v_lshlrev_b64 v[178:179], 1, v[156:157]
	v_lshl_add_u64 v[46:47], v[156:157], 2, s[2:3]
	v_lshl_add_u64 v[156:157], v[158:159], 0, v[178:179]
	v_lshl_add_u64 v[158:159], v[160:161], 2, s[12:13]
	v_lshrrev_b32_e32 v156, 5, v182
	v_mov_b32_e32 v157, 0
	v_lshlrev_b32_e32 v48, 7, v156
	v_mov_b32_e32 v49, 0
	v_lshl_add_u64 v[46:47], v[46:47], 0, v[48:49]
	global_load_dwordx4 v[208:211], v[46:47], off
	global_load_dwordx4 v[212:215], v[46:47], off offset:16
	global_load_dwordx4 v[216:219], v[46:47], off offset:128
	global_load_dwordx4 v[220:223], v[46:47], off offset:144
	global_load_dword v200, v[158:159], off
	global_load_dword v201, v[158:159], off offset:64
	global_load_dword v202, v[158:159], off offset:128
	global_load_dword v203, v[158:159], off offset:192
	global_load_dword v204, v[158:159], off offset:512
	global_load_dword v205, v[158:159], off offset:576
	global_load_dword v206, v[158:159], off offset:640
	global_load_dword v207, v[158:159], off offset:704
	s_mov_b32 s17, 0x800000
	v_and_b32_e32 v184, 0xfffffff7, v160
	v_ashrrev_i32_e32 v185, 31, v184
	v_lshlrev_b64 v[184:185], 13, v[184:185]
	v_lshl_add_u64 v[184:185], s[86:87], 0, v[184:185]
	v_lshlrev_b32_e32 v156, 6, v156
	v_and_b32_e32 v48, 24, v182
	v_or_b32_e32 v156, v156, v48
	v_bfe_u32 v48, v160, 3, 1
	v_lshl_or_b32 v156, v48, 5, v156
	v_lshl_or_b32 v156, s37, 8, v156
	v_lshlrev_b32_e32 v156, 1, v156
	v_lshl_add_u64 v[184:185], v[184:185], 0, v[156:157]
	s_waitcnt vmcnt(0)
; DI unsigned pk2(float lo, float hi) { return pg8::cvt_pk_bf16(lo, hi); }
;     DI void operator()(const f32x4 (&acc)[2][2][4][2], const Unit& u, int wr, int wc, int fr, int fq) const {
;     ...
;         for (int ai = 0; ai < 2; ++ai)
; #pragma unroll
;             for (int m = 0; m < 4; ++m) { bf16* rowp = O + (size_t)(row0 + ai * 128 + m * 16) * 4096 + col0;
;                 const float rstd = rsqrtf(rowss[row0 + ai * 128 + m * 16] * (1.0f / 1024.0f) + 1e-6f);
; #pragma unroll
;                 for (int bj = 0; bj < 2; ++bj) { f32x4 v0 = acc[ai][bj][m][0] * rstd + bs[bj][0], v1 = acc[ai][bj][m][1] * rstd + bs[bj][1];
; #pragma unroll
;                     for (int i = 0; i < 4; ++i) { float a = fmaxf(v0[i], 0.f), b = fmaxf(v1[i], 0.f); v0[i] = a * a; v1[i] = b * b; }
;                     v4u w; w.x = pk2(v0[0], v0[1]); w.y = pk2(v0[2], v0[3]); w.z = pk2(v1[0], v1[1]); w.w = pk2(v1[2], v1[3]);
;                     *(v4u*)(rowp + bj * 128) = w; } }
	v_fmamk_f32 v224, v200, 0x3a800000, v192
	v_cmp_gt_f32_e32 vcc, s17, v224
	v_mul_f32_e32 v225, 0x4b800000, v224
	s_nop 0
	v_cndmask_b32_e32 v224, v224, v225, vcc
	v_rsq_f32_e32 v224, v224
	s_nop 0
	v_mul_f32_e32 v225, 0x45800000, v224
	v_cndmask_b32_e32 v224, v224, v225, vcc
	v_pk_fma_f32 v[142:143], v[142:143], v[224:225], v[208:209] op_sel_hi:[1,0,1]
	v_pk_fma_f32 v[144:145], v[144:145], v[224:225], v[210:211] op_sel_hi:[1,0,1]
	v_pk_fma_f32 v[138:139], v[138:139], v[224:225], v[212:213] op_sel_hi:[1,0,1]
	v_pk_fma_f32 v[140:141], v[140:141], v[224:225], v[214:215] op_sel_hi:[1,0,1]
	v_max_f32_e32 v142, 0, v142
	v_max_f32_e32 v143, 0, v143
	v_max_f32_e32 v144, 0, v144
	v_max_f32_e32 v145, 0, v145
	v_max_f32_e32 v138, 0, v138
	v_max_f32_e32 v139, 0, v139
	v_max_f32_e32 v140, 0, v140
	v_max_f32_e32 v141, 0, v141
	v_mul_f32_e32 v142, v142, v142
	v_mul_f32_e32 v143, v143, v143
	v_mul_f32_e32 v144, v144, v144
	v_mul_f32_e32 v145, v145, v145
	v_mul_f32_e32 v138, v138, v138
	v_mul_f32_e32 v139, v139, v139
	v_mul_f32_e32 v140, v140, v140
	v_mul_f32_e32 v141, v141, v141
	v_cvt_pk_bf16_f32 v226, v142, v143
	v_cvt_pk_bf16_f32 v227, v144, v145
	v_cvt_pk_bf16_f32 v228, v138, v139
	v_cvt_pk_bf16_f32 v229, v140, v141
	v_pk_fma_f32 v[134:135], v[134:135], v[224:225], v[216:217] op_sel_hi:[1,0,1]
	v_pk_fma_f32 v[136:137], v[136:137], v[224:225], v[218:219] op_sel_hi:[1,0,1]
	v_pk_fma_f32 v[130:131], v[130:131], v[224:225], v[220:221] op_sel_hi:[1,0,1]
	v_pk_fma_f32 v[132:133], v[132:133], v[224:225], v[222:223] op_sel_hi:[1,0,1]
	v_max_f32_e32 v134, 0, v134
	v_max_f32_e32 v135, 0, v135
	v_max_f32_e32 v136, 0, v136
	v_max_f32_e32 v137, 0, v137
	v_max_f32_e32 v130, 0, v130
	v_max_f32_e32 v131, 0, v131
	v_max_f32_e32 v132, 0, v132
	v_max_f32_e32 v133, 0, v133
	v_mul_f32_e32 v134, v134, v134
	v_mul_f32_e32 v135, v135, v135
	v_mul_f32_e32 v136, v136, v136
	v_mul_f32_e32 v137, v137, v137
	v_mul_f32_e32 v130, v130, v130
	v_mul_f32_e32 v131, v131, v131
	v_mul_f32_e32 v132, v132, v132
	v_mul_f32_e32 v133, v133, v133
	v_cvt_pk_bf16_f32 v230, v134, v135
	v_cvt_pk_bf16_f32 v231, v136, v137
	v_cvt_pk_bf16_f32 v232, v130, v131
	v_cvt_pk_bf16_f32 v233, v132, v133
	v_mov_b32_e32 v234, v230
	v_mov_b32_e32 v235, v231
	v_mov_b32_e32 v236, v232
	v_mov_b32_e32 v237, v233
	v_mov_b32_dpp v230, v226 row_shl:8 row_mask:0xf bank_mask:0x3
	v_mov_b32_dpp v231, v227 row_shl:8 row_mask:0xf bank_mask:0x3
	v_mov_b32_dpp v232, v228 row_shl:8 row_mask:0xf bank_mask:0x3
	v_mov_b32_dpp v233, v229 row_shl:8 row_mask:0xf bank_mask:0x3
	v_mov_b32_dpp v226, v234 row_shr:8 row_mask:0xf bank_mask:0xc
	v_mov_b32_dpp v227, v235 row_shr:8 row_mask:0xf bank_mask:0xc
	v_mov_b32_dpp v228, v236 row_shr:8 row_mask:0xf bank_mask:0xc
	v_mov_b32_dpp v229, v237 row_shr:8 row_mask:0xf bank_mask:0xc
	s_mov_b64 s[98:99], 0x10000
	v_lshl_add_u64 v[238:239], v[184:185], 0, s[98:99]
	global_store_dwordx4 v[184:185], v[226:229], off
	global_store_dwordx4 v[238:239], v[230:233], off
	v_fmamk_f32 v224, v201, 0x3a800000, v192
	v_cmp_gt_f32_e32 vcc, s17, v224
	v_mul_f32_e32 v225, 0x4b800000, v224
	s_nop 0
	v_cndmask_b32_e32 v224, v224, v225, vcc
	v_rsq_f32_e32 v224, v224
	s_nop 0
	v_mul_f32_e32 v225, 0x45800000, v224
	v_cndmask_b32_e32 v224, v224, v225, vcc
	v_pk_fma_f32 v[126:127], v[126:127], v[224:225], v[208:209] op_sel_hi:[1,0,1]
	v_pk_fma_f32 v[128:129], v[128:129], v[224:225], v[210:211] op_sel_hi:[1,0,1]
	v_pk_fma_f32 v[122:123], v[122:123], v[224:225], v[212:213] op_sel_hi:[1,0,1]
	v_pk_fma_f32 v[124:125], v[124:125], v[224:225], v[214:215] op_sel_hi:[1,0,1]
	v_max_f32_e32 v126, 0, v126
	v_max_f32_e32 v127, 0, v127
	v_max_f32_e32 v128, 0, v128
	v_max_f32_e32 v129, 0, v129
	v_max_f32_e32 v122, 0, v122
	v_max_f32_e32 v123, 0, v123
	v_max_f32_e32 v124, 0, v124
	v_max_f32_e32 v125, 0, v125
	v_mul_f32_e32 v126, v126, v126
	v_mul_f32_e32 v127, v127, v127
	v_mul_f32_e32 v128, v128, v128
	v_mul_f32_e32 v129, v129, v129
	v_mul_f32_e32 v122, v122, v122
	v_mul_f32_e32 v123, v123, v123
	v_mul_f32_e32 v124, v124, v124
	v_mul_f32_e32 v125, v125, v125
	v_cvt_pk_bf16_f32 v58, v126, v127
	v_cvt_pk_bf16_f32 v59, v128, v129
	v_cvt_pk_bf16_f32 v60, v122, v123
	v_cvt_pk_bf16_f32 v61, v124, v125
	v_pk_fma_f32 v[118:119], v[118:119], v[224:225], v[216:217] op_sel_hi:[1,0,1]
	v_pk_fma_f32 v[120:121], v[120:121], v[224:225], v[218:219] op_sel_hi:[1,0,1]
	v_pk_fma_f32 v[114:115], v[114:115], v[224:225], v[220:221] op_sel_hi:[1,0,1]
	v_pk_fma_f32 v[116:117], v[116:117], v[224:225], v[222:223] op_sel_hi:[1,0,1]
	v_max_f32_e32 v118, 0, v118
	v_max_f32_e32 v119, 0, v119
	v_max_f32_e32 v120, 0, v120
	v_max_f32_e32 v121, 0, v121
	v_max_f32_e32 v114, 0, v114
	v_max_f32_e32 v115, 0, v115
	v_max_f32_e32 v116, 0, v116
	v_max_f32_e32 v117, 0, v117
	v_mul_f32_e32 v118, v118, v118
	v_mul_f32_e32 v119, v119, v119
	v_mul_f32_e32 v120, v120, v120
	v_mul_f32_e32 v121, v121, v121
	v_mul_f32_e32 v114, v114, v114
	v_mul_f32_e32 v115, v115, v115
	v_mul_f32_e32 v116, v116, v116
	v_mul_f32_e32 v117, v117, v117
	v_cvt_pk_bf16_f32 v62, v118, v119
	v_cvt_pk_bf16_f32 v63, v120, v121
	v_cvt_pk_bf16_f32 v64, v114, v115
	v_cvt_pk_bf16_f32 v65, v116, v117
	v_mov_b32_e32 v42, v62
	v_mov_b32_e32 v43, v63
	v_mov_b32_e32 v44, v64
	v_mov_b32_e32 v45, v65
	v_mov_b32_dpp v62, v58 row_shl:8 row_mask:0xf bank_mask:0x3
	v_mov_b32_dpp v63, v59 row_shl:8 row_mask:0xf bank_mask:0x3
	v_mov_b32_dpp v64, v60 row_shl:8 row_mask:0xf bank_mask:0x3
	v_mov_b32_dpp v65, v61 row_shl:8 row_mask:0xf bank_mask:0x3
	v_mov_b32_dpp v58, v42 row_shr:8 row_mask:0xf bank_mask:0xc
	v_mov_b32_dpp v59, v43 row_shr:8 row_mask:0xf bank_mask:0xc
	v_mov_b32_dpp v60, v44 row_shr:8 row_mask:0xf bank_mask:0xc
; DI unsigned pk2(float lo, float hi) { return pg8::cvt_pk_bf16(lo, hi); }
;     DI void operator()(const f32x4 (&acc)[2][2][4][2], const Unit& u, int wr, int wc, int fr, int fq) const {
;     ...
;         for (int ai = 0; ai < 2; ++ai)
; #pragma unroll
;             for (int m = 0; m < 4; ++m) { bf16* rowp = O + (size_t)(row0 + ai * 128 + m * 16) * 4096 + col0;
;                 const float rstd = rsqrtf(rowss[row0 + ai * 128 + m * 16] * (1.0f / 1024.0f) + 1e-6f);
; #pragma unroll
;                 for (int bj = 0; bj < 2; ++bj) { f32x4 v0 = acc[ai][bj][m][0] * rstd + bs[bj][0], v1 = acc[ai][bj][m][1] * rstd + bs[bj][1];
; #pragma unroll
;                     for (int i = 0; i < 4; ++i) { float a = fmaxf(v0[i], 0.f), b = fmaxf(v1[i], 0.f); v0[i] = a * a; v1[i] = b * b; }
;                     v4u w; w.x = pk2(v0[0], v0[1]); w.y = pk2(v0[2], v0[3]); w.z = pk2(v1[0], v1[1]); w.w = pk2(v1[2], v1[3]);
;                     *(v4u*)(rowp + bj * 128) = w; } }
	v_mov_b32_dpp v61, v45 row_shr:8 row_mask:0xf bank_mask:0xc
	s_mov_b64 s[98:99], 0x20000
	v_lshl_add_u64 v[186:187], v[184:185], 0, s[98:99]
	s_mov_b64 s[98:99], 0x30000
	v_lshl_add_u64 v[238:239], v[184:185], 0, s[98:99]
	global_store_dwordx4 v[186:187], v[58:61], off
	global_store_dwordx4 v[238:239], v[62:65], off
	v_fmamk_f32 v224, v202, 0x3a800000, v192
	v_cmp_gt_f32_e32 vcc, s17, v224
	v_mul_f32_e32 v225, 0x4b800000, v224
	s_nop 0
	v_cndmask_b32_e32 v224, v224, v225, vcc
	v_rsq_f32_e32 v224, v224
	s_nop 0
	v_mul_f32_e32 v225, 0x45800000, v224
	v_cndmask_b32_e32 v224, v224, v225, vcc
	v_pk_fma_f32 v[110:111], v[110:111], v[224:225], v[208:209] op_sel_hi:[1,0,1]
	v_pk_fma_f32 v[112:113], v[112:113], v[224:225], v[210:211] op_sel_hi:[1,0,1]
	v_pk_fma_f32 v[106:107], v[106:107], v[224:225], v[212:213] op_sel_hi:[1,0,1]
	v_pk_fma_f32 v[108:109], v[108:109], v[224:225], v[214:215] op_sel_hi:[1,0,1]
	v_max_f32_e32 v110, 0, v110
	v_max_f32_e32 v111, 0, v111
	v_max_f32_e32 v112, 0, v112
	v_max_f32_e32 v113, 0, v113
	v_max_f32_e32 v106, 0, v106
	v_max_f32_e32 v107, 0, v107
	v_max_f32_e32 v108, 0, v108
	v_max_f32_e32 v109, 0, v109
	v_mul_f32_e32 v110, v110, v110
	v_mul_f32_e32 v111, v111, v111
	v_mul_f32_e32 v112, v112, v112
	v_mul_f32_e32 v113, v113, v113
	v_mul_f32_e32 v106, v106, v106
	v_mul_f32_e32 v107, v107, v107
	v_mul_f32_e32 v108, v108, v108
	v_mul_f32_e32 v109, v109, v109
	v_cvt_pk_bf16_f32 v226, v110, v111
	v_cvt_pk_bf16_f32 v227, v112, v113
	v_cvt_pk_bf16_f32 v228, v106, v107
	v_cvt_pk_bf16_f32 v229, v108, v109
	v_pk_fma_f32 v[102:103], v[102:103], v[224:225], v[216:217] op_sel_hi:[1,0,1]
	v_pk_fma_f32 v[104:105], v[104:105], v[224:225], v[218:219] op_sel_hi:[1,0,1]
	v_pk_fma_f32 v[98:99], v[98:99], v[224:225], v[220:221] op_sel_hi:[1,0,1]
	v_pk_fma_f32 v[100:101], v[100:101], v[224:225], v[222:223] op_sel_hi:[1,0,1]
	v_max_f32_e32 v102, 0, v102
	v_max_f32_e32 v103, 0, v103
	v_max_f32_e32 v104, 0, v104
	v_max_f32_e32 v105, 0, v105
	v_max_f32_e32 v98, 0, v98
	v_max_f32_e32 v99, 0, v99
	v_max_f32_e32 v100, 0, v100
	v_max_f32_e32 v101, 0, v101
	v_mul_f32_e32 v102, v102, v102
	v_mul_f32_e32 v103, v103, v103
	v_mul_f32_e32 v104, v104, v104
	v_mul_f32_e32 v105, v105, v105
	v_mul_f32_e32 v98, v98, v98
	v_mul_f32_e32 v99, v99, v99
	v_mul_f32_e32 v100, v100, v100
	v_mul_f32_e32 v101, v101, v101
	v_cvt_pk_bf16_f32 v230, v102, v103
	v_cvt_pk_bf16_f32 v231, v104, v105
	v_cvt_pk_bf16_f32 v232, v98, v99
	v_cvt_pk_bf16_f32 v233, v100, v101
	v_mov_b32_e32 v234, v230
	v_mov_b32_e32 v235, v231
	v_mov_b32_e32 v236, v232
	v_mov_b32_e32 v237, v233
	v_mov_b32_dpp v230, v226 row_shl:8 row_mask:0xf bank_mask:0x3
	v_mov_b32_dpp v231, v227 row_shl:8 row_mask:0xf bank_mask:0x3
	v_mov_b32_dpp v232, v228 row_shl:8 row_mask:0xf bank_mask:0x3
	v_mov_b32_dpp v233, v229 row_shl:8 row_mask:0xf bank_mask:0x3
	v_mov_b32_dpp v226, v234 row_shr:8 row_mask:0xf bank_mask:0xc
	v_mov_b32_dpp v227, v235 row_shr:8 row_mask:0xf bank_mask:0xc
	v_mov_b32_dpp v228, v236 row_shr:8 row_mask:0xf bank_mask:0xc
	v_mov_b32_dpp v229, v237 row_shr:8 row_mask:0xf bank_mask:0xc
	s_mov_b64 s[98:99], 0x40000
	v_lshl_add_u64 v[186:187], v[184:185], 0, s[98:99]
	s_mov_b64 s[98:99], 0x50000
	v_lshl_add_u64 v[238:239], v[184:185], 0, s[98:99]
	global_store_dwordx4 v[186:187], v[226:229], off
	global_store_dwordx4 v[238:239], v[230:233], off
	v_fmamk_f32 v224, v203, 0x3a800000, v192
	v_cmp_gt_f32_e32 vcc, s17, v224
	v_mul_f32_e32 v225, 0x4b800000, v224
	s_nop 0
	v_cndmask_b32_e32 v224, v224, v225, vcc
	v_rsq_f32_e32 v224, v224
	s_nop 0
	v_mul_f32_e32 v225, 0x45800000, v224
	v_cndmask_b32_e32 v224, v224, v225, vcc
	v_pk_fma_f32 v[94:95], v[94:95], v[224:225], v[208:209] op_sel_hi:[1,0,1]
	v_pk_fma_f32 v[96:97], v[96:97], v[224:225], v[210:211] op_sel_hi:[1,0,1]
	v_pk_fma_f32 v[90:91], v[90:91], v[224:225], v[212:213] op_sel_hi:[1,0,1]
	v_pk_fma_f32 v[92:93], v[92:93], v[224:225], v[214:215] op_sel_hi:[1,0,1]
	v_max_f32_e32 v94, 0, v94
	v_max_f32_e32 v95, 0, v95
	v_max_f32_e32 v96, 0, v96
	v_max_f32_e32 v97, 0, v97
	v_max_f32_e32 v90, 0, v90
	v_max_f32_e32 v91, 0, v91
	v_max_f32_e32 v92, 0, v92
	v_max_f32_e32 v93, 0, v93
	v_mul_f32_e32 v94, v94, v94
	v_mul_f32_e32 v95, v95, v95
	v_mul_f32_e32 v96, v96, v96
	v_mul_f32_e32 v97, v97, v97
	v_mul_f32_e32 v90, v90, v90
	v_mul_f32_e32 v91, v91, v91
	v_mul_f32_e32 v92, v92, v92
	v_mul_f32_e32 v93, v93, v93
	v_cvt_pk_bf16_f32 v58, v94, v95
	v_cvt_pk_bf16_f32 v59, v96, v97
	v_cvt_pk_bf16_f32 v60, v90, v91
	v_cvt_pk_bf16_f32 v61, v92, v93
	v_pk_fma_f32 v[86:87], v[86:87], v[224:225], v[216:217] op_sel_hi:[1,0,1]
	v_pk_fma_f32 v[88:89], v[88:89], v[224:225], v[218:219] op_sel_hi:[1,0,1]
	v_pk_fma_f32 v[82:83], v[82:83], v[224:225], v[220:221] op_sel_hi:[1,0,1]
	v_pk_fma_f32 v[84:85], v[84:85], v[224:225], v[222:223] op_sel_hi:[1,0,1]
	v_max_f32_e32 v86, 0, v86
	v_max_f32_e32 v87, 0, v87
	v_max_f32_e32 v88, 0, v88
	v_max_f32_e32 v89, 0, v89
	v_max_f32_e32 v82, 0, v82
	v_max_f32_e32 v83, 0, v83
	v_max_f32_e32 v84, 0, v84
	v_max_f32_e32 v85, 0, v85
	v_mul_f32_e32 v86, v86, v86
	v_mul_f32_e32 v87, v87, v87
	v_mul_f32_e32 v88, v88, v88
	v_mul_f32_e32 v89, v89, v89
	v_mul_f32_e32 v82, v82, v82
	v_mul_f32_e32 v83, v83, v83
	v_mul_f32_e32 v84, v84, v84
	v_mul_f32_e32 v85, v85, v85
	v_cvt_pk_bf16_f32 v62, v86, v87
	v_cvt_pk_bf16_f32 v63, v88, v89
	v_cvt_pk_bf16_f32 v64, v82, v83
	v_cvt_pk_bf16_f32 v65, v84, v85
	v_mov_b32_e32 v42, v62
	v_mov_b32_e32 v43, v63
	v_mov_b32_e32 v44, v64
	v_mov_b32_e32 v45, v65
	v_mov_b32_dpp v62, v58 row_shl:8 row_mask:0xf bank_mask:0x3
	v_mov_b32_dpp v63, v59 row_shl:8 row_mask:0xf bank_mask:0x3
	v_mov_b32_dpp v64, v60 row_shl:8 row_mask:0xf bank_mask:0x3
; DI unsigned pk2(float lo, float hi) { return pg8::cvt_pk_bf16(lo, hi); }
;     DI void operator()(const f32x4 (&acc)[2][2][4][2], const Unit& u, int wr, int wc, int fr, int fq) const {
;     ...
;         for (int ai = 0; ai < 2; ++ai)
; #pragma unroll
;             for (int m = 0; m < 4; ++m) { bf16* rowp = O + (size_t)(row0 + ai * 128 + m * 16) * 4096 + col0;
;                 const float rstd = rsqrtf(rowss[row0 + ai * 128 + m * 16] * (1.0f / 1024.0f) + 1e-6f);
; #pragma unroll
;                 for (int bj = 0; bj < 2; ++bj) { f32x4 v0 = acc[ai][bj][m][0] * rstd + bs[bj][0], v1 = acc[ai][bj][m][1] * rstd + bs[bj][1];
; #pragma unroll
;                     for (int i = 0; i < 4; ++i) { float a = fmaxf(v0[i], 0.f), b = fmaxf(v1[i], 0.f); v0[i] = a * a; v1[i] = b * b; }
;                     v4u w; w.x = pk2(v0[0], v0[1]); w.y = pk2(v0[2], v0[3]); w.z = pk2(v1[0], v1[1]); w.w = pk2(v1[2], v1[3]);
;                     *(v4u*)(rowp + bj * 128) = w; } }
	v_mov_b32_dpp v65, v61 row_shl:8 row_mask:0xf bank_mask:0x3
	v_mov_b32_dpp v58, v42 row_shr:8 row_mask:0xf bank_mask:0xc
	v_mov_b32_dpp v59, v43 row_shr:8 row_mask:0xf bank_mask:0xc
	v_mov_b32_dpp v60, v44 row_shr:8 row_mask:0xf bank_mask:0xc
	v_mov_b32_dpp v61, v45 row_shr:8 row_mask:0xf bank_mask:0xc
	s_mov_b64 s[98:99], 0x60000
	v_lshl_add_u64 v[186:187], v[184:185], 0, s[98:99]
	s_mov_b64 s[98:99], 0x70000
	v_lshl_add_u64 v[238:239], v[184:185], 0, s[98:99]
	global_store_dwordx4 v[186:187], v[58:61], off
	global_store_dwordx4 v[238:239], v[62:65], off
	v_fmamk_f32 v224, v204, 0x3a800000, v192
	v_cmp_gt_f32_e32 vcc, s17, v224
	v_mul_f32_e32 v225, 0x4b800000, v224
	s_nop 0
	v_cndmask_b32_e32 v224, v224, v225, vcc
	v_rsq_f32_e32 v224, v224
	s_nop 0
	v_mul_f32_e32 v225, 0x45800000, v224
	v_cndmask_b32_e32 v224, v224, v225, vcc
	v_pk_fma_f32 v[78:79], v[78:79], v[224:225], v[208:209] op_sel_hi:[1,0,1]
	v_pk_fma_f32 v[80:81], v[80:81], v[224:225], v[210:211] op_sel_hi:[1,0,1]
	v_pk_fma_f32 v[74:75], v[74:75], v[224:225], v[212:213] op_sel_hi:[1,0,1]
	v_pk_fma_f32 v[76:77], v[76:77], v[224:225], v[214:215] op_sel_hi:[1,0,1]
	v_max_f32_e32 v78, 0, v78
	v_max_f32_e32 v79, 0, v79
	v_max_f32_e32 v80, 0, v80
	v_max_f32_e32 v81, 0, v81
	v_max_f32_e32 v74, 0, v74
	v_max_f32_e32 v75, 0, v75
	v_max_f32_e32 v76, 0, v76
	v_max_f32_e32 v77, 0, v77
	v_mul_f32_e32 v78, v78, v78
	v_mul_f32_e32 v79, v79, v79
	v_mul_f32_e32 v80, v80, v80
	v_mul_f32_e32 v81, v81, v81
	v_mul_f32_e32 v74, v74, v74
	v_mul_f32_e32 v75, v75, v75
	v_mul_f32_e32 v76, v76, v76
	v_mul_f32_e32 v77, v77, v77
	v_cvt_pk_bf16_f32 v226, v78, v79
	v_cvt_pk_bf16_f32 v227, v80, v81
	v_cvt_pk_bf16_f32 v228, v74, v75
	v_cvt_pk_bf16_f32 v229, v76, v77
	v_pk_fma_f32 v[70:71], v[70:71], v[224:225], v[216:217] op_sel_hi:[1,0,1]
	v_pk_fma_f32 v[72:73], v[72:73], v[224:225], v[218:219] op_sel_hi:[1,0,1]
	v_pk_fma_f32 v[66:67], v[66:67], v[224:225], v[220:221] op_sel_hi:[1,0,1]
	v_pk_fma_f32 v[68:69], v[68:69], v[224:225], v[222:223] op_sel_hi:[1,0,1]
	v_max_f32_e32 v70, 0, v70
	v_max_f32_e32 v71, 0, v71
	v_max_f32_e32 v72, 0, v72
	v_max_f32_e32 v73, 0, v73
	v_max_f32_e32 v66, 0, v66
	v_max_f32_e32 v67, 0, v67
	v_max_f32_e32 v68, 0, v68
	v_max_f32_e32 v69, 0, v69
	v_mul_f32_e32 v70, v70, v70
	v_mul_f32_e32 v71, v71, v71
	v_mul_f32_e32 v72, v72, v72
	v_mul_f32_e32 v73, v73, v73
	v_mul_f32_e32 v66, v66, v66
	v_mul_f32_e32 v67, v67, v67
	v_mul_f32_e32 v68, v68, v68
	v_mul_f32_e32 v69, v69, v69
	v_cvt_pk_bf16_f32 v230, v70, v71
	v_cvt_pk_bf16_f32 v231, v72, v73
	v_cvt_pk_bf16_f32 v232, v66, v67
	v_cvt_pk_bf16_f32 v233, v68, v69
	v_mov_b32_e32 v234, v230
	v_mov_b32_e32 v235, v231
	v_mov_b32_e32 v236, v232
	v_mov_b32_e32 v237, v233
	v_mov_b32_dpp v230, v226 row_shl:8 row_mask:0xf bank_mask:0x3
	v_mov_b32_dpp v231, v227 row_shl:8 row_mask:0xf bank_mask:0x3
	v_mov_b32_dpp v232, v228 row_shl:8 row_mask:0xf bank_mask:0x3
	v_mov_b32_dpp v233, v229 row_shl:8 row_mask:0xf bank_mask:0x3
	v_mov_b32_dpp v226, v234 row_shr:8 row_mask:0xf bank_mask:0xc
	v_mov_b32_dpp v227, v235 row_shr:8 row_mask:0xf bank_mask:0xc
	v_mov_b32_dpp v228, v236 row_shr:8 row_mask:0xf bank_mask:0xc
	v_mov_b32_dpp v229, v237 row_shr:8 row_mask:0xf bank_mask:0xc
	s_mov_b64 s[98:99], 0x100000
	v_lshl_add_u64 v[186:187], v[184:185], 0, s[98:99]
	s_mov_b64 s[98:99], 0x110000
	v_lshl_add_u64 v[238:239], v[184:185], 0, s[98:99]
	global_store_dwordx4 v[186:187], v[226:229], off
	global_store_dwordx4 v[238:239], v[230:233], off
	v_fmamk_f32 v224, v205, 0x3a800000, v192
	v_cmp_gt_f32_e32 vcc, s17, v224
	v_mul_f32_e32 v225, 0x4b800000, v224
	s_nop 0
	v_cndmask_b32_e32 v224, v224, v225, vcc
	v_rsq_f32_e32 v224, v224
	s_nop 0
	v_mul_f32_e32 v225, 0x45800000, v224
	v_cndmask_b32_e32 v224, v224, v225, vcc
	v_pk_fma_f32 v[54:55], v[54:55], v[224:225], v[208:209] op_sel_hi:[1,0,1]
	v_pk_fma_f32 v[56:57], v[56:57], v[224:225], v[210:211] op_sel_hi:[1,0,1]
	v_pk_fma_f32 v[50:51], v[50:51], v[224:225], v[212:213] op_sel_hi:[1,0,1]
	v_pk_fma_f32 v[52:53], v[52:53], v[224:225], v[214:215] op_sel_hi:[1,0,1]
	v_max_f32_e32 v54, 0, v54
	v_max_f32_e32 v55, 0, v55
	v_max_f32_e32 v56, 0, v56
	v_max_f32_e32 v57, 0, v57
	v_max_f32_e32 v50, 0, v50
	v_max_f32_e32 v51, 0, v51
	v_max_f32_e32 v52, 0, v52
	v_max_f32_e32 v53, 0, v53
	v_mul_f32_e32 v54, v54, v54
	v_mul_f32_e32 v55, v55, v55
	v_mul_f32_e32 v56, v56, v56
	v_mul_f32_e32 v57, v57, v57
	v_mul_f32_e32 v50, v50, v50
	v_mul_f32_e32 v51, v51, v51
	v_mul_f32_e32 v52, v52, v52
	v_mul_f32_e32 v53, v53, v53
	v_cvt_pk_bf16_f32 v58, v54, v55
	v_cvt_pk_bf16_f32 v59, v56, v57
	v_cvt_pk_bf16_f32 v60, v50, v51
	v_cvt_pk_bf16_f32 v61, v52, v53
	v_pk_fma_f32 v[38:39], v[38:39], v[224:225], v[216:217] op_sel_hi:[1,0,1]
	v_pk_fma_f32 v[40:41], v[40:41], v[224:225], v[218:219] op_sel_hi:[1,0,1]
	v_pk_fma_f32 v[34:35], v[34:35], v[224:225], v[220:221] op_sel_hi:[1,0,1]
	v_pk_fma_f32 v[36:37], v[36:37], v[224:225], v[222:223] op_sel_hi:[1,0,1]
	v_max_f32_e32 v38, 0, v38
	v_max_f32_e32 v39, 0, v39
	v_max_f32_e32 v40, 0, v40
	v_max_f32_e32 v41, 0, v41
	v_max_f32_e32 v34, 0, v34
	v_max_f32_e32 v35, 0, v35
	v_max_f32_e32 v36, 0, v36
	v_max_f32_e32 v37, 0, v37
	v_mul_f32_e32 v38, v38, v38
	v_mul_f32_e32 v39, v39, v39
	v_mul_f32_e32 v40, v40, v40
	v_mul_f32_e32 v41, v41, v41
	v_mul_f32_e32 v34, v34, v34
	v_mul_f32_e32 v35, v35, v35
	v_mul_f32_e32 v36, v36, v36
	v_mul_f32_e32 v37, v37, v37
	v_cvt_pk_bf16_f32 v62, v38, v39
	v_cvt_pk_bf16_f32 v63, v40, v41
	v_cvt_pk_bf16_f32 v64, v34, v35
	v_cvt_pk_bf16_f32 v65, v36, v37
	v_mov_b32_e32 v42, v62
	v_mov_b32_e32 v43, v63
	v_mov_b32_e32 v44, v64
	v_mov_b32_e32 v45, v65
; DI unsigned pk2(float lo, float hi) { return pg8::cvt_pk_bf16(lo, hi); }
;     DI void operator()(const f32x4 (&acc)[2][2][4][2], const Unit& u, int wr, int wc, int fr, int fq) const {
;     ...
;         for (int ai = 0; ai < 2; ++ai)
; #pragma unroll
;             for (int m = 0; m < 4; ++m) { bf16* rowp = O + (size_t)(row0 + ai * 128 + m * 16) * 4096 + col0;
;                 const float rstd = rsqrtf(rowss[row0 + ai * 128 + m * 16] * (1.0f / 1024.0f) + 1e-6f);
; #pragma unroll
;                 for (int bj = 0; bj < 2; ++bj) { f32x4 v0 = acc[ai][bj][m][0] * rstd + bs[bj][0], v1 = acc[ai][bj][m][1] * rstd + bs[bj][1];
; #pragma unroll
;                     for (int i = 0; i < 4; ++i) { float a = fmaxf(v0[i], 0.f), b = fmaxf(v1[i], 0.f); v0[i] = a * a; v1[i] = b * b; }
;                     v4u w; w.x = pk2(v0[0], v0[1]); w.y = pk2(v0[2], v0[3]); w.z = pk2(v1[0], v1[1]); w.w = pk2(v1[2], v1[3]);
;                     *(v4u*)(rowp + bj * 128) = w; } }
	v_mov_b32_dpp v62, v58 row_shl:8 row_mask:0xf bank_mask:0x3
	v_mov_b32_dpp v63, v59 row_shl:8 row_mask:0xf bank_mask:0x3
	v_mov_b32_dpp v64, v60 row_shl:8 row_mask:0xf bank_mask:0x3
	v_mov_b32_dpp v65, v61 row_shl:8 row_mask:0xf bank_mask:0x3
	v_mov_b32_dpp v58, v42 row_shr:8 row_mask:0xf bank_mask:0xc
	v_mov_b32_dpp v59, v43 row_shr:8 row_mask:0xf bank_mask:0xc
	v_mov_b32_dpp v60, v44 row_shr:8 row_mask:0xf bank_mask:0xc
	v_mov_b32_dpp v61, v45 row_shr:8 row_mask:0xf bank_mask:0xc
	s_mov_b64 s[98:99], 0x120000
	v_lshl_add_u64 v[186:187], v[184:185], 0, s[98:99]
	s_mov_b64 s[98:99], 0x130000
	v_lshl_add_u64 v[238:239], v[184:185], 0, s[98:99]
	global_store_dwordx4 v[186:187], v[58:61], off
	global_store_dwordx4 v[238:239], v[62:65], off
	v_fmamk_f32 v224, v206, 0x3a800000, v192
	v_cmp_gt_f32_e32 vcc, s17, v224
	v_mul_f32_e32 v225, 0x4b800000, v224
	s_nop 0
	v_cndmask_b32_e32 v224, v224, v225, vcc
	v_rsq_f32_e32 v224, v224
	s_nop 0
	v_mul_f32_e32 v225, 0x45800000, v224
	v_cndmask_b32_e32 v224, v224, v225, vcc
	v_pk_fma_f32 v[30:31], v[30:31], v[224:225], v[208:209] op_sel_hi:[1,0,1]
	v_pk_fma_f32 v[32:33], v[32:33], v[224:225], v[210:211] op_sel_hi:[1,0,1]
	v_pk_fma_f32 v[26:27], v[26:27], v[224:225], v[212:213] op_sel_hi:[1,0,1]
	v_pk_fma_f32 v[28:29], v[28:29], v[224:225], v[214:215] op_sel_hi:[1,0,1]
	v_max_f32_e32 v30, 0, v30
	v_max_f32_e32 v31, 0, v31
	v_max_f32_e32 v32, 0, v32
	v_max_f32_e32 v33, 0, v33
	v_max_f32_e32 v26, 0, v26
	v_max_f32_e32 v27, 0, v27
	v_max_f32_e32 v28, 0, v28
	v_max_f32_e32 v29, 0, v29
	v_mul_f32_e32 v30, v30, v30
	v_mul_f32_e32 v31, v31, v31
	v_mul_f32_e32 v32, v32, v32
	v_mul_f32_e32 v33, v33, v33
	v_mul_f32_e32 v26, v26, v26
	v_mul_f32_e32 v27, v27, v27
	v_mul_f32_e32 v28, v28, v28
	v_mul_f32_e32 v29, v29, v29
	v_cvt_pk_bf16_f32 v226, v30, v31
	v_cvt_pk_bf16_f32 v227, v32, v33
	v_cvt_pk_bf16_f32 v228, v26, v27
	v_cvt_pk_bf16_f32 v229, v28, v29
	v_pk_fma_f32 v[22:23], v[22:23], v[224:225], v[216:217] op_sel_hi:[1,0,1]
	v_pk_fma_f32 v[24:25], v[24:25], v[224:225], v[218:219] op_sel_hi:[1,0,1]
	v_pk_fma_f32 v[18:19], v[18:19], v[224:225], v[220:221] op_sel_hi:[1,0,1]
	v_pk_fma_f32 v[20:21], v[20:21], v[224:225], v[222:223] op_sel_hi:[1,0,1]
	v_max_f32_e32 v22, 0, v22
	v_max_f32_e32 v23, 0, v23
	v_max_f32_e32 v24, 0, v24
	v_max_f32_e32 v25, 0, v25
	v_max_f32_e32 v18, 0, v18
	v_max_f32_e32 v19, 0, v19
	v_max_f32_e32 v20, 0, v20
	v_max_f32_e32 v21, 0, v21
	v_mul_f32_e32 v22, v22, v22
	v_mul_f32_e32 v23, v23, v23
	v_mul_f32_e32 v24, v24, v24
	v_mul_f32_e32 v25, v25, v25
	v_mul_f32_e32 v18, v18, v18
	v_mul_f32_e32 v19, v19, v19
	v_mul_f32_e32 v20, v20, v20
	v_mul_f32_e32 v21, v21, v21
	v_cvt_pk_bf16_f32 v230, v22, v23
	v_cvt_pk_bf16_f32 v231, v24, v25
	v_cvt_pk_bf16_f32 v232, v18, v19
	v_cvt_pk_bf16_f32 v233, v20, v21
	v_mov_b32_e32 v234, v230
	v_mov_b32_e32 v235, v231
	v_mov_b32_e32 v236, v232
	v_mov_b32_e32 v237, v233
	v_mov_b32_dpp v230, v226 row_shl:8 row_mask:0xf bank_mask:0x3
	v_mov_b32_dpp v231, v227 row_shl:8 row_mask:0xf bank_mask:0x3
	v_mov_b32_dpp v232, v228 row_shl:8 row_mask:0xf bank_mask:0x3
	v_mov_b32_dpp v233, v229 row_shl:8 row_mask:0xf bank_mask:0x3
	v_mov_b32_dpp v226, v234 row_shr:8 row_mask:0xf bank_mask:0xc
	v_mov_b32_dpp v227, v235 row_shr:8 row_mask:0xf bank_mask:0xc
	v_mov_b32_dpp v228, v236 row_shr:8 row_mask:0xf bank_mask:0xc
	v_mov_b32_dpp v229, v237 row_shr:8 row_mask:0xf bank_mask:0xc
	s_mov_b64 s[98:99], 0x140000
	v_lshl_add_u64 v[186:187], v[184:185], 0, s[98:99]
	s_mov_b64 s[98:99], 0x150000
	v_lshl_add_u64 v[238:239], v[184:185], 0, s[98:99]
	global_store_dwordx4 v[186:187], v[226:229], off
	global_store_dwordx4 v[238:239], v[230:233], off
	v_fmamk_f32 v224, v207, 0x3a800000, v192
	v_cmp_gt_f32_e32 vcc, s17, v224
	v_mul_f32_e32 v225, 0x4b800000, v224
	s_nop 0
	v_cndmask_b32_e32 v224, v224, v225, vcc
	v_rsq_f32_e32 v224, v224
	s_nop 0
	v_mul_f32_e32 v225, 0x45800000, v224
	v_cndmask_b32_e32 v224, v224, v225, vcc
	v_pk_fma_f32 v[14:15], v[14:15], v[224:225], v[208:209] op_sel_hi:[1,0,1]
	v_pk_fma_f32 v[16:17], v[16:17], v[224:225], v[210:211] op_sel_hi:[1,0,1]
	v_pk_fma_f32 v[10:11], v[10:11], v[224:225], v[212:213] op_sel_hi:[1,0,1]
	v_pk_fma_f32 v[12:13], v[12:13], v[224:225], v[214:215] op_sel_hi:[1,0,1]
	v_max_f32_e32 v14, 0, v14
	v_max_f32_e32 v15, 0, v15
	v_max_f32_e32 v16, 0, v16
	v_max_f32_e32 v17, 0, v17
	v_max_f32_e32 v10, 0, v10
	v_max_f32_e32 v11, 0, v11
	v_max_f32_e32 v12, 0, v12
	v_max_f32_e32 v13, 0, v13
	v_mul_f32_e32 v14, v14, v14
	v_mul_f32_e32 v15, v15, v15
	v_mul_f32_e32 v16, v16, v16
	v_mul_f32_e32 v17, v17, v17
	v_mul_f32_e32 v10, v10, v10
	v_mul_f32_e32 v11, v11, v11
	v_mul_f32_e32 v12, v12, v12
	v_mul_f32_e32 v13, v13, v13
	v_cvt_pk_bf16_f32 v58, v14, v15
	v_cvt_pk_bf16_f32 v59, v16, v17
	v_cvt_pk_bf16_f32 v60, v10, v11
	v_cvt_pk_bf16_f32 v61, v12, v13
	v_pk_fma_f32 v[6:7], v[6:7], v[224:225], v[216:217] op_sel_hi:[1,0,1]
	v_pk_fma_f32 v[8:9], v[8:9], v[224:225], v[218:219] op_sel_hi:[1,0,1]
	v_pk_fma_f32 v[2:3], v[2:3], v[224:225], v[220:221] op_sel_hi:[1,0,1]
	v_pk_fma_f32 v[4:5], v[4:5], v[224:225], v[222:223] op_sel_hi:[1,0,1]
	v_max_f32_e32 v6, 0, v6
	v_max_f32_e32 v7, 0, v7
	v_max_f32_e32 v8, 0, v8
	v_max_f32_e32 v9, 0, v9
	v_max_f32_e32 v2, 0, v2
	v_max_f32_e32 v3, 0, v3
	v_max_f32_e32 v4, 0, v4
	v_max_f32_e32 v5, 0, v5
	v_mul_f32_e32 v6, v6, v6
	v_mul_f32_e32 v7, v7, v7
	v_mul_f32_e32 v8, v8, v8
	v_mul_f32_e32 v9, v9, v9
	v_mul_f32_e32 v2, v2, v2
	v_mul_f32_e32 v3, v3, v3
	v_mul_f32_e32 v4, v4, v4
	v_mul_f32_e32 v5, v5, v5
	v_cvt_pk_bf16_f32 v62, v6, v7
	v_cvt_pk_bf16_f32 v63, v8, v9
	v_cvt_pk_bf16_f32 v64, v2, v3
	v_cvt_pk_bf16_f32 v65, v4, v5
	v_mov_b32_e32 v42, v62
	v_mov_b32_e32 v43, v63
	v_mov_b32_e32 v44, v64
	v_mov_b32_e32 v45, v65
	v_mov_b32_dpp v62, v58 row_shl:8 row_mask:0xf bank_mask:0x3
	v_mov_b32_dpp v63, v59 row_shl:8 row_mask:0xf bank_mask:0x3
	v_mov_b32_dpp v64, v60 row_shl:8 row_mask:0xf bank_mask:0x3
	v_mov_b32_dpp v65, v61 row_shl:8 row_mask:0xf bank_mask:0x3
	v_mov_b32_dpp v58, v42 row_shr:8 row_mask:0xf bank_mask:0xc
	v_mov_b32_dpp v59, v43 row_shr:8 row_mask:0xf bank_mask:0xc
	v_mov_b32_dpp v60, v44 row_shr:8 row_mask:0xf bank_mask:0xc
	v_mov_b32_dpp v61, v45 row_shr:8 row_mask:0xf bank_mask:0xc
	s_mov_b64 s[98:99], 0x160000
	v_lshl_add_u64 v[186:187], v[184:185], 0, s[98:99]
	s_mov_b64 s[98:99], 0x170000
	v_lshl_add_u64 v[238:239], v[184:185], 0, s[98:99]
	global_store_dwordx4 v[186:187], v[58:61], off
	global_store_dwordx4 v[238:239], v[62:65], off
	s_mov_b64 s[2:3], -1
	s_andn2_b64 vcc, exec, s[4:5]
	s_cbranch_vccnz .LBB0_731
	s_andn2_b64 vcc, exec, s[6:7]
	s_cbranch_vccnz .LBB0_730
	s_barrier
	s_branch .LBB0_730

;     DI void operator()(const f32x4 (&acc)[2][2][4][2], const Unit& u, int wr, int wc, int fr, int fq) const {
;     ...
;         const int b = (grow0 + u.pm * 256) >> 11;
;         f32x4 g[2][2];
; #pragma unroll
;         for (int bj = 0; bj < 2; ++bj) { const float* gp = gate + (size_t)b * 6144 + col0 + bj * 128; g[bj][0] = *(const f32x4*)gp; g[bj][1] = *(const f32x4*)(gp + 4); }
; #pragma unroll
;         for (int ai = 0; ai < 2; ++ai)
; #pragma unroll
;             for (int m = 0; m < 4; ++m) { const size_t r = (size_t)(row0 + ai * 128 + m * 16);
; #pragma unroll
;                 for (int bj = 0; bj < 2; ++bj) { const size_t off = r * 1024 + col0 + bj * 128;
;                     f32x4 v0 = *(const f32x4*)(base + off), v1 = *(const f32x4*)(base + off + 4);
;                     v0 += g[bj][0] * acc[ai][bj][m][0]; v1 += g[bj][1] * acc[ai][bj][m][1];
;                     *(f32x4*)(out + off) = v0; *(f32x4*)(out + off + 4) = v1; } }
.LBB0_815:
	s_lshl_b32 s7, s31, 8
	v_readlane_b32 s16, v254, 56
	s_add_i32 s11, s7, s16
	v_readlane_b32 s17, v254, 57
	s_ashr_i32 s11, s11, 11
	v_add_u32_e32 v164, s7, v158
	v_lshl_or_b32 v50, s30, 8, v160
	s_mul_hi_i32 s17, s11, 0x6000
	s_mulk_i32 s11, 0x6000
	v_readlane_b32 s16, v252, 33
	v_ashrrev_i32_e32 v165, 31, v164
	s_add_u32 s16, s16, s11
	v_readlane_b32 s11, v252, 34
	v_ashrrev_i32_e32 v51, 31, v50
	v_lshlrev_b64 v[156:157], 12, v[164:165]
	s_addc_u32 s17, s11, s17
	v_lshlrev_b64 v[162:163], 2, v[50:51]
	v_lshl_add_u64 v[156:157], s[8:9], 0, v[156:157]
	v_lshl_add_u64 v[54:55], s[16:17], 0, v[162:163]
	v_lshl_add_u64 v[156:157], v[156:157], 0, v[162:163]
	global_load_dwordx4 v[74:77], v[54:55], off offset:16
	global_load_dwordx4 v[78:81], v[54:55], off
	global_load_dwordx4 v[50:53], v[54:55], off offset:528
	s_nop 0
	global_load_dwordx4 v[54:57], v[54:55], off offset:512
	v_bfe_u32 v184, v164, 3, 1
	v_sub_u32_e32 v185, 0, v184
	v_mul_i32_i24_e32 v184, 0x7ff0, v185
	v_lshl_add_u64 v[200:201], v[156:157], 0, v[184:185]
	s_mov_b64 s[98:99], 0x0
	v_lshl_add_u64 v[202:203], v[200:201], 0, s[98:99]
	s_mov_b64 s[98:99], 0x8000
	v_lshl_add_u64 v[178:179], v[200:201], 0, s[98:99]
	global_load_dwordx4 v[208:211], v[202:203], off
	global_load_dwordx4 v[212:215], v[178:179], off
	global_load_dwordx4 v[216:219], v[202:203], off offset:512
	global_load_dwordx4 v[220:223], v[178:179], off offset:512
	s_mov_b64 s[98:99], 0x10000
	v_lshl_add_u64 v[202:203], v[200:201], 0, s[98:99]
	s_mov_b64 s[98:99], 0x18000
	v_lshl_add_u64 v[178:179], v[200:201], 0, s[98:99]
	global_load_dwordx4 v[224:227], v[202:203], off
	global_load_dwordx4 v[228:231], v[178:179], off
	global_load_dwordx4 v[232:235], v[202:203], off offset:512
	global_load_dwordx4 v[236:239], v[178:179], off offset:512
	s_waitcnt vmcnt(6)
	v_mov_b32_e32 v204, v208
	v_mov_b32_e32 v205, v209
	v_mov_b32_e32 v206, v210
	v_mov_b32_e32 v207, v211
	v_mov_b32_dpp v208, v212 row_shr:8 row_mask:0xf bank_mask:0xc
	v_mov_b32_dpp v209, v213 row_shr:8 row_mask:0xf bank_mask:0xc
	v_mov_b32_dpp v210, v214 row_shr:8 row_mask:0xf bank_mask:0xc
	v_mov_b32_dpp v211, v215 row_shr:8 row_mask:0xf bank_mask:0xc
	v_mov_b32_dpp v212, v204 row_shl:8 row_mask:0xf bank_mask:0x3
	v_mov_b32_dpp v213, v205 row_shl:8 row_mask:0xf bank_mask:0x3
	v_mov_b32_dpp v214, v206 row_shl:8 row_mask:0xf bank_mask:0x3
	v_mov_b32_dpp v215, v207 row_shl:8 row_mask:0xf bank_mask:0x3
	v_pk_fma_f32 v[208:209], v[142:143], v[78:79], v[208:209]
	v_pk_fma_f32 v[210:211], v[144:145], v[80:81], v[210:211]
	v_pk_fma_f32 v[212:213], v[138:139], v[74:75], v[212:213]
	v_pk_fma_f32 v[214:215], v[140:141], v[76:77], v[214:215]
	v_mov_b32_e32 v204, v212
	v_mov_b32_e32 v205, v213
	v_mov_b32_e32 v206, v214
	v_mov_b32_e32 v207, v215
	v_mov_b32_dpp v212, v208 row_shl:8 row_mask:0xf bank_mask:0x3
	v_mov_b32_dpp v213, v209 row_shl:8 row_mask:0xf bank_mask:0x3
	v_mov_b32_dpp v214, v210 row_shl:8 row_mask:0xf bank_mask:0x3
	v_mov_b32_dpp v215, v211 row_shl:8 row_mask:0xf bank_mask:0x3
	v_mov_b32_dpp v208, v204 row_shr:8 row_mask:0xf bank_mask:0xc
	v_mov_b32_dpp v209, v205 row_shr:8 row_mask:0xf bank_mask:0xc
	v_mov_b32_dpp v210, v206 row_shr:8 row_mask:0xf bank_mask:0xc
	v_mov_b32_dpp v211, v207 row_shr:8 row_mask:0xf bank_mask:0xc
	s_mov_b64 s[98:99], 0x0
	v_lshl_add_u64 v[180:181], v[200:201], 0, s[98:99]
	s_mov_b64 s[98:99], 0x8000
	v_lshl_add_u64 v[182:183], v[200:201], 0, s[98:99]
	global_store_dwordx4 v[180:181], v[208:211], off
	global_store_dwordx4 v[182:183], v[212:215], off
	s_nop 1
	s_mov_b64 s[98:99], 0x20000
	v_lshl_add_u64 v[202:203], v[200:201], 0, s[98:99]
	s_mov_b64 s[98:99], 0x28000
	v_lshl_add_u64 v[178:179], v[200:201], 0, s[98:99]
	global_load_dwordx4 v[208:211], v[202:203], off
	global_load_dwordx4 v[212:215], v[178:179], off
	s_waitcnt vmcnt(8)
	v_mov_b32_e32 v204, v216
	v_mov_b32_e32 v205, v217
	v_mov_b32_e32 v206, v218
	v_mov_b32_e32 v207, v219
	v_mov_b32_dpp v216, v220 row_shr:8 row_mask:0xf bank_mask:0xc
	v_mov_b32_dpp v217, v221 row_shr:8 row_mask:0xf bank_mask:0xc
	v_mov_b32_dpp v218, v222 row_shr:8 row_mask:0xf bank_mask:0xc
	v_mov_b32_dpp v219, v223 row_shr:8 row_mask:0xf bank_mask:0xc
	v_mov_b32_dpp v220, v204 row_shl:8 row_mask:0xf bank_mask:0x3
	v_mov_b32_dpp v221, v205 row_shl:8 row_mask:0xf bank_mask:0x3
	v_mov_b32_dpp v222, v206 row_shl:8 row_mask:0xf bank_mask:0x3
	v_mov_b32_dpp v223, v207 row_shl:8 row_mask:0xf bank_mask:0x3
	v_pk_fma_f32 v[216:217], v[134:135], v[54:55], v[216:217]
	v_pk_fma_f32 v[218:219], v[136:137], v[56:57], v[218:219]
	v_pk_fma_f32 v[220:221], v[130:131], v[50:51], v[220:221]
	v_pk_fma_f32 v[222:223], v[132:133], v[52:53], v[222:223]
	v_mov_b32_e32 v204, v220
	v_mov_b32_e32 v205, v221
	v_mov_b32_e32 v206, v222
	v_mov_b32_e32 v207, v223
	v_mov_b32_dpp v220, v216 row_shl:8 row_mask:0xf bank_mask:0x3
	v_mov_b32_dpp v221, v217 row_shl:8 row_mask:0xf bank_mask:0x3
	v_mov_b32_dpp v222, v218 row_shl:8 row_mask:0xf bank_mask:0x3
	v_mov_b32_dpp v223, v219 row_shl:8 row_mask:0xf bank_mask:0x3
	v_mov_b32_dpp v216, v204 row_shr:8 row_mask:0xf bank_mask:0xc
	v_mov_b32_dpp v217, v205 row_shr:8 row_mask:0xf bank_mask:0xc
	v_mov_b32_dpp v218, v206 row_shr:8 row_mask:0xf bank_mask:0xc
	v_mov_b32_dpp v219, v207 row_shr:8 row_mask:0xf bank_mask:0xc
	global_store_dwordx4 v[180:181], v[216:219], off offset:512
	global_store_dwordx4 v[182:183], v[220:223], off offset:512
	s_nop 1
	global_load_dwordx4 v[216:219], v[202:203], off offset:512
	global_load_dwordx4 v[220:223], v[178:179], off offset:512
	s_waitcnt vmcnt(10)
;     DI void operator()(const f32x4 (&acc)[2][2][4][2], const Unit& u, int wr, int wc, int fr, int fq) const {
;     ...
;         for (int ai = 0; ai < 2; ++ai)
; #pragma unroll
;             for (int m = 0; m < 4; ++m) { const size_t r = (size_t)(row0 + ai * 128 + m * 16);
; #pragma unroll
;                 for (int bj = 0; bj < 2; ++bj) { const size_t off = r * 1024 + col0 + bj * 128;
;                     f32x4 v0 = *(const f32x4*)(base + off), v1 = *(const f32x4*)(base + off + 4);
;                     v0 += g[bj][0] * acc[ai][bj][m][0]; v1 += g[bj][1] * acc[ai][bj][m][1];
;                     *(f32x4*)(out + off) = v0; *(f32x4*)(out + off + 4) = v1; } }
	v_mov_b32_e32 v204, v224
	v_mov_b32_e32 v205, v225
	v_mov_b32_e32 v206, v226
	v_mov_b32_e32 v207, v227
	v_mov_b32_dpp v224, v228 row_shr:8 row_mask:0xf bank_mask:0xc
	v_mov_b32_dpp v225, v229 row_shr:8 row_mask:0xf bank_mask:0xc
	v_mov_b32_dpp v226, v230 row_shr:8 row_mask:0xf bank_mask:0xc
	v_mov_b32_dpp v227, v231 row_shr:8 row_mask:0xf bank_mask:0xc
	v_mov_b32_dpp v228, v204 row_shl:8 row_mask:0xf bank_mask:0x3
	v_mov_b32_dpp v229, v205 row_shl:8 row_mask:0xf bank_mask:0x3
	v_mov_b32_dpp v230, v206 row_shl:8 row_mask:0xf bank_mask:0x3
	v_mov_b32_dpp v231, v207 row_shl:8 row_mask:0xf bank_mask:0x3
	v_pk_fma_f32 v[224:225], v[126:127], v[78:79], v[224:225]
	v_pk_fma_f32 v[226:227], v[128:129], v[80:81], v[226:227]
	v_pk_fma_f32 v[228:229], v[122:123], v[74:75], v[228:229]
	v_pk_fma_f32 v[230:231], v[124:125], v[76:77], v[230:231]
	v_mov_b32_e32 v204, v228
	v_mov_b32_e32 v205, v229
	v_mov_b32_e32 v206, v230
	v_mov_b32_e32 v207, v231
	v_mov_b32_dpp v228, v224 row_shl:8 row_mask:0xf bank_mask:0x3
	v_mov_b32_dpp v229, v225 row_shl:8 row_mask:0xf bank_mask:0x3
	v_mov_b32_dpp v230, v226 row_shl:8 row_mask:0xf bank_mask:0x3
	v_mov_b32_dpp v231, v227 row_shl:8 row_mask:0xf bank_mask:0x3
	v_mov_b32_dpp v224, v204 row_shr:8 row_mask:0xf bank_mask:0xc
	v_mov_b32_dpp v225, v205 row_shr:8 row_mask:0xf bank_mask:0xc
	v_mov_b32_dpp v226, v206 row_shr:8 row_mask:0xf bank_mask:0xc
	v_mov_b32_dpp v227, v207 row_shr:8 row_mask:0xf bank_mask:0xc
	s_mov_b64 s[98:99], 0x10000
	v_lshl_add_u64 v[180:181], v[200:201], 0, s[98:99]
	s_mov_b64 s[98:99], 0x18000
	v_lshl_add_u64 v[182:183], v[200:201], 0, s[98:99]
	global_store_dwordx4 v[180:181], v[224:227], off
	global_store_dwordx4 v[182:183], v[228:231], off
	s_nop 1
	s_mov_b64 s[98:99], 0x30000
	v_lshl_add_u64 v[202:203], v[200:201], 0, s[98:99]
	s_mov_b64 s[98:99], 0x38000
	v_lshl_add_u64 v[178:179], v[200:201], 0, s[98:99]
	global_load_dwordx4 v[224:227], v[202:203], off
	global_load_dwordx4 v[228:231], v[178:179], off
	s_waitcnt vmcnt(12)
	v_mov_b32_e32 v204, v232
	v_mov_b32_e32 v205, v233
	v_mov_b32_e32 v206, v234
	v_mov_b32_e32 v207, v235
	v_mov_b32_dpp v232, v236 row_shr:8 row_mask:0xf bank_mask:0xc
	v_mov_b32_dpp v233, v237 row_shr:8 row_mask:0xf bank_mask:0xc
	v_mov_b32_dpp v234, v238 row_shr:8 row_mask:0xf bank_mask:0xc
	v_mov_b32_dpp v235, v239 row_shr:8 row_mask:0xf bank_mask:0xc
	v_mov_b32_dpp v236, v204 row_shl:8 row_mask:0xf bank_mask:0x3
	v_mov_b32_dpp v237, v205 row_shl:8 row_mask:0xf bank_mask:0x3
	v_mov_b32_dpp v238, v206 row_shl:8 row_mask:0xf bank_mask:0x3
	v_mov_b32_dpp v239, v207 row_shl:8 row_mask:0xf bank_mask:0x3
	v_pk_fma_f32 v[232:233], v[110:111], v[54:55], v[232:233]
	v_pk_fma_f32 v[234:235], v[112:113], v[56:57], v[234:235]
	v_pk_fma_f32 v[236:237], v[106:107], v[50:51], v[236:237]
	v_pk_fma_f32 v[238:239], v[108:109], v[52:53], v[238:239]
	v_mov_b32_e32 v204, v236
	v_mov_b32_e32 v205, v237
	v_mov_b32_e32 v206, v238
	v_mov_b32_e32 v207, v239
	v_mov_b32_dpp v236, v232 row_shl:8 row_mask:0xf bank_mask:0x3
	v_mov_b32_dpp v237, v233 row_shl:8 row_mask:0xf bank_mask:0x3
	v_mov_b32_dpp v238, v234 row_shl:8 row_mask:0xf bank_mask:0x3
	v_mov_b32_dpp v239, v235 row_shl:8 row_mask:0xf bank_mask:0x3
	v_mov_b32_dpp v232, v204 row_shr:8 row_mask:0xf bank_mask:0xc
	v_mov_b32_dpp v233, v205 row_shr:8 row_mask:0xf bank_mask:0xc
	v_mov_b32_dpp v234, v206 row_shr:8 row_mask:0xf bank_mask:0xc
	v_mov_b32_dpp v235, v207 row_shr:8 row_mask:0xf bank_mask:0xc
	global_store_dwordx4 v[180:181], v[232:235], off offset:512
	global_store_dwordx4 v[182:183], v[236:239], off offset:512
	s_nop 1
	global_load_dwordx4 v[232:235], v[202:203], off offset:512
	global_load_dwordx4 v[236:239], v[178:179], off offset:512
	s_waitcnt vmcnt(12)
	v_mov_b32_e32 v204, v208
	v_mov_b32_e32 v205, v209
	v_mov_b32_e32 v206, v210
	v_mov_b32_e32 v207, v211
	v_mov_b32_dpp v208, v212 row_shr:8 row_mask:0xf bank_mask:0xc
	v_mov_b32_dpp v209, v213 row_shr:8 row_mask:0xf bank_mask:0xc
	v_mov_b32_dpp v210, v214 row_shr:8 row_mask:0xf bank_mask:0xc
	v_mov_b32_dpp v211, v215 row_shr:8 row_mask:0xf bank_mask:0xc
	v_mov_b32_dpp v212, v204 row_shl:8 row_mask:0xf bank_mask:0x3
	v_mov_b32_dpp v213, v205 row_shl:8 row_mask:0xf bank_mask:0x3
	v_mov_b32_dpp v214, v206 row_shl:8 row_mask:0xf bank_mask:0x3
	v_mov_b32_dpp v215, v207 row_shl:8 row_mask:0xf bank_mask:0x3
	v_pk_fma_f32 v[208:209], v[118:119], v[78:79], v[208:209]
	v_pk_fma_f32 v[210:211], v[120:121], v[80:81], v[210:211]
	v_pk_fma_f32 v[212:213], v[114:115], v[74:75], v[212:213]
	v_pk_fma_f32 v[214:215], v[116:117], v[76:77], v[214:215]
	v_mov_b32_e32 v204, v212
	v_mov_b32_e32 v205, v213
	v_mov_b32_e32 v206, v214
	v_mov_b32_e32 v207, v215
	v_mov_b32_dpp v212, v208 row_shl:8 row_mask:0xf bank_mask:0x3
	v_mov_b32_dpp v213, v209 row_shl:8 row_mask:0xf bank_mask:0x3
	v_mov_b32_dpp v214, v210 row_shl:8 row_mask:0xf bank_mask:0x3
	v_mov_b32_dpp v215, v211 row_shl:8 row_mask:0xf bank_mask:0x3
	v_mov_b32_dpp v208, v204 row_shr:8 row_mask:0xf bank_mask:0xc
	v_mov_b32_dpp v209, v205 row_shr:8 row_mask:0xf bank_mask:0xc
	v_mov_b32_dpp v210, v206 row_shr:8 row_mask:0xf bank_mask:0xc
	v_mov_b32_dpp v211, v207 row_shr:8 row_mask:0xf bank_mask:0xc
	s_mov_b64 s[98:99], 0x20000
	v_lshl_add_u64 v[180:181], v[200:201], 0, s[98:99]
	s_mov_b64 s[98:99], 0x28000
	v_lshl_add_u64 v[182:183], v[200:201], 0, s[98:99]
	global_store_dwordx4 v[180:181], v[208:211], off
	global_store_dwordx4 v[182:183], v[212:215], off
	s_nop 1
	s_mov_b64 s[98:99], 0x80000
	v_lshl_add_u64 v[202:203], v[200:201], 0, s[98:99]
	s_mov_b64 s[98:99], 0x88000
	v_lshl_add_u64 v[178:179], v[200:201], 0, s[98:99]
	global_load_dwordx4 v[208:211], v[202:203], off
	global_load_dwordx4 v[212:215], v[178:179], off
	s_waitcnt vmcnt(12)
;     DI void operator()(const f32x4 (&acc)[2][2][4][2], const Unit& u, int wr, int wc, int fr, int fq) const {
;     ...
;         for (int ai = 0; ai < 2; ++ai)
; #pragma unroll
;             for (int m = 0; m < 4; ++m) { const size_t r = (size_t)(row0 + ai * 128 + m * 16);
; #pragma unroll
;                 for (int bj = 0; bj < 2; ++bj) { const size_t off = r * 1024 + col0 + bj * 128;
;                     f32x4 v0 = *(const f32x4*)(base + off), v1 = *(const f32x4*)(base + off + 4);
;                     v0 += g[bj][0] * acc[ai][bj][m][0]; v1 += g[bj][1] * acc[ai][bj][m][1];
;                     *(f32x4*)(out + off) = v0; *(f32x4*)(out + off + 4) = v1; } }
	v_mov_b32_e32 v204, v216
	v_mov_b32_e32 v205, v217
	v_mov_b32_e32 v206, v218
	v_mov_b32_e32 v207, v219
	v_mov_b32_dpp v216, v220 row_shr:8 row_mask:0xf bank_mask:0xc
	v_mov_b32_dpp v217, v221 row_shr:8 row_mask:0xf bank_mask:0xc
	v_mov_b32_dpp v218, v222 row_shr:8 row_mask:0xf bank_mask:0xc
	v_mov_b32_dpp v219, v223 row_shr:8 row_mask:0xf bank_mask:0xc
	v_mov_b32_dpp v220, v204 row_shl:8 row_mask:0xf bank_mask:0x3
	v_mov_b32_dpp v221, v205 row_shl:8 row_mask:0xf bank_mask:0x3
	v_mov_b32_dpp v222, v206 row_shl:8 row_mask:0xf bank_mask:0x3
	v_mov_b32_dpp v223, v207 row_shl:8 row_mask:0xf bank_mask:0x3
	v_pk_fma_f32 v[216:217], v[94:95], v[54:55], v[216:217]
	v_pk_fma_f32 v[218:219], v[96:97], v[56:57], v[218:219]
	v_pk_fma_f32 v[220:221], v[90:91], v[50:51], v[220:221]
	v_pk_fma_f32 v[222:223], v[92:93], v[52:53], v[222:223]
	v_mov_b32_e32 v204, v220
	v_mov_b32_e32 v205, v221
	v_mov_b32_e32 v206, v222
	v_mov_b32_e32 v207, v223
	v_mov_b32_dpp v220, v216 row_shl:8 row_mask:0xf bank_mask:0x3
	v_mov_b32_dpp v221, v217 row_shl:8 row_mask:0xf bank_mask:0x3
	v_mov_b32_dpp v222, v218 row_shl:8 row_mask:0xf bank_mask:0x3
	v_mov_b32_dpp v223, v219 row_shl:8 row_mask:0xf bank_mask:0x3
	v_mov_b32_dpp v216, v204 row_shr:8 row_mask:0xf bank_mask:0xc
	v_mov_b32_dpp v217, v205 row_shr:8 row_mask:0xf bank_mask:0xc
	v_mov_b32_dpp v218, v206 row_shr:8 row_mask:0xf bank_mask:0xc
	v_mov_b32_dpp v219, v207 row_shr:8 row_mask:0xf bank_mask:0xc
	global_store_dwordx4 v[180:181], v[216:219], off offset:512
	global_store_dwordx4 v[182:183], v[220:223], off offset:512
	s_nop 1
	global_load_dwordx4 v[216:219], v[202:203], off offset:512
	global_load_dwordx4 v[220:223], v[178:179], off offset:512
	s_waitcnt vmcnt(12)
	v_mov_b32_e32 v204, v224
	v_mov_b32_e32 v205, v225
	v_mov_b32_e32 v206, v226
	v_mov_b32_e32 v207, v227
	v_mov_b32_dpp v224, v228 row_shr:8 row_mask:0xf bank_mask:0xc
	v_mov_b32_dpp v225, v229 row_shr:8 row_mask:0xf bank_mask:0xc
	v_mov_b32_dpp v226, v230 row_shr:8 row_mask:0xf bank_mask:0xc
	v_mov_b32_dpp v227, v231 row_shr:8 row_mask:0xf bank_mask:0xc
	v_mov_b32_dpp v228, v204 row_shl:8 row_mask:0xf bank_mask:0x3
	v_mov_b32_dpp v229, v205 row_shl:8 row_mask:0xf bank_mask:0x3
	v_mov_b32_dpp v230, v206 row_shl:8 row_mask:0xf bank_mask:0x3
	v_mov_b32_dpp v231, v207 row_shl:8 row_mask:0xf bank_mask:0x3
	v_pk_fma_f32 v[224:225], v[102:103], v[78:79], v[224:225]
	v_pk_fma_f32 v[226:227], v[104:105], v[80:81], v[226:227]
	v_pk_fma_f32 v[228:229], v[98:99], v[74:75], v[228:229]
	v_pk_fma_f32 v[230:231], v[100:101], v[76:77], v[230:231]
	v_mov_b32_e32 v204, v228
	v_mov_b32_e32 v205, v229
	v_mov_b32_e32 v206, v230
	v_mov_b32_e32 v207, v231
	v_mov_b32_dpp v228, v224 row_shl:8 row_mask:0xf bank_mask:0x3
	v_mov_b32_dpp v229, v225 row_shl:8 row_mask:0xf bank_mask:0x3
	v_mov_b32_dpp v230, v226 row_shl:8 row_mask:0xf bank_mask:0x3
	v_mov_b32_dpp v231, v227 row_shl:8 row_mask:0xf bank_mask:0x3
	v_mov_b32_dpp v224, v204 row_shr:8 row_mask:0xf bank_mask:0xc
	v_mov_b32_dpp v225, v205 row_shr:8 row_mask:0xf bank_mask:0xc
	v_mov_b32_dpp v226, v206 row_shr:8 row_mask:0xf bank_mask:0xc
	v_mov_b32_dpp v227, v207 row_shr:8 row_mask:0xf bank_mask:0xc
	s_mov_b64 s[98:99], 0x30000
	v_lshl_add_u64 v[180:181], v[200:201], 0, s[98:99]
	s_mov_b64 s[98:99], 0x38000
	v_lshl_add_u64 v[182:183], v[200:201], 0, s[98:99]
	global_store_dwordx4 v[180:181], v[224:227], off
	global_store_dwordx4 v[182:183], v[228:231], off
	s_nop 1
	s_mov_b64 s[98:99], 0x90000
	v_lshl_add_u64 v[202:203], v[200:201], 0, s[98:99]
	s_mov_b64 s[98:99], 0x98000
	v_lshl_add_u64 v[178:179], v[200:201], 0, s[98:99]
	global_load_dwordx4 v[224:227], v[202:203], off
	global_load_dwordx4 v[228:231], v[178:179], off
	s_waitcnt vmcnt(12)
	v_mov_b32_e32 v204, v232
	v_mov_b32_e32 v205, v233
	v_mov_b32_e32 v206, v234
	v_mov_b32_e32 v207, v235
	v_mov_b32_dpp v232, v236 row_shr:8 row_mask:0xf bank_mask:0xc
	v_mov_b32_dpp v233, v237 row_shr:8 row_mask:0xf bank_mask:0xc
	v_mov_b32_dpp v234, v238 row_shr:8 row_mask:0xf bank_mask:0xc
	v_mov_b32_dpp v235, v239 row_shr:8 row_mask:0xf bank_mask:0xc
	v_mov_b32_dpp v236, v204 row_shl:8 row_mask:0xf bank_mask:0x3
	v_mov_b32_dpp v237, v205 row_shl:8 row_mask:0xf bank_mask:0x3
	v_mov_b32_dpp v238, v206 row_shl:8 row_mask:0xf bank_mask:0x3
	v_mov_b32_dpp v239, v207 row_shl:8 row_mask:0xf bank_mask:0x3
	v_pk_fma_f32 v[232:233], v[86:87], v[54:55], v[232:233]
	v_pk_fma_f32 v[234:235], v[88:89], v[56:57], v[234:235]
	v_pk_fma_f32 v[236:237], v[82:83], v[50:51], v[236:237]
	v_pk_fma_f32 v[238:239], v[84:85], v[52:53], v[238:239]
	v_mov_b32_e32 v204, v236
	v_mov_b32_e32 v205, v237
	v_mov_b32_e32 v206, v238
	v_mov_b32_e32 v207, v239
	v_mov_b32_dpp v236, v232 row_shl:8 row_mask:0xf bank_mask:0x3
	v_mov_b32_dpp v237, v233 row_shl:8 row_mask:0xf bank_mask:0x3
	v_mov_b32_dpp v238, v234 row_shl:8 row_mask:0xf bank_mask:0x3
	v_mov_b32_dpp v239, v235 row_shl:8 row_mask:0xf bank_mask:0x3
	v_mov_b32_dpp v232, v204 row_shr:8 row_mask:0xf bank_mask:0xc
	v_mov_b32_dpp v233, v205 row_shr:8 row_mask:0xf bank_mask:0xc
	v_mov_b32_dpp v234, v206 row_shr:8 row_mask:0xf bank_mask:0xc
	v_mov_b32_dpp v235, v207 row_shr:8 row_mask:0xf bank_mask:0xc
	global_store_dwordx4 v[180:181], v[232:235], off offset:512
	global_store_dwordx4 v[182:183], v[236:239], off offset:512
	s_nop 1
	global_load_dwordx4 v[232:235], v[202:203], off offset:512
	global_load_dwordx4 v[236:239], v[178:179], off offset:512
	s_waitcnt vmcnt(12)
;     DI void operator()(const f32x4 (&acc)[2][2][4][2], const Unit& u, int wr, int wc, int fr, int fq) const {
;     ...
;         for (int ai = 0; ai < 2; ++ai)
; #pragma unroll
;             for (int m = 0; m < 4; ++m) { const size_t r = (size_t)(row0 + ai * 128 + m * 16);
; #pragma unroll
;                 for (int bj = 0; bj < 2; ++bj) { const size_t off = r * 1024 + col0 + bj * 128;
;                     f32x4 v0 = *(const f32x4*)(base + off), v1 = *(const f32x4*)(base + off + 4);
;                     v0 += g[bj][0] * acc[ai][bj][m][0]; v1 += g[bj][1] * acc[ai][bj][m][1];
;                     *(f32x4*)(out + off) = v0; *(f32x4*)(out + off + 4) = v1; } }
	v_mov_b32_e32 v204, v208
	v_mov_b32_e32 v205, v209
	v_mov_b32_e32 v206, v210
	v_mov_b32_e32 v207, v211
	v_mov_b32_dpp v208, v212 row_shr:8 row_mask:0xf bank_mask:0xc
	v_mov_b32_dpp v209, v213 row_shr:8 row_mask:0xf bank_mask:0xc
	v_mov_b32_dpp v210, v214 row_shr:8 row_mask:0xf bank_mask:0xc
	v_mov_b32_dpp v211, v215 row_shr:8 row_mask:0xf bank_mask:0xc
	v_mov_b32_dpp v212, v204 row_shl:8 row_mask:0xf bank_mask:0x3
	v_mov_b32_dpp v213, v205 row_shl:8 row_mask:0xf bank_mask:0x3
	v_mov_b32_dpp v214, v206 row_shl:8 row_mask:0xf bank_mask:0x3
	v_mov_b32_dpp v215, v207 row_shl:8 row_mask:0xf bank_mask:0x3
	v_pk_fma_f32 v[208:209], v[70:71], v[78:79], v[208:209]
	v_pk_fma_f32 v[210:211], v[72:73], v[80:81], v[210:211]
	v_pk_fma_f32 v[212:213], v[66:67], v[74:75], v[212:213]
	v_pk_fma_f32 v[214:215], v[68:69], v[76:77], v[214:215]
	v_mov_b32_e32 v204, v212
	v_mov_b32_e32 v205, v213
	v_mov_b32_e32 v206, v214
	v_mov_b32_e32 v207, v215
	v_mov_b32_dpp v212, v208 row_shl:8 row_mask:0xf bank_mask:0x3
	v_mov_b32_dpp v213, v209 row_shl:8 row_mask:0xf bank_mask:0x3
	v_mov_b32_dpp v214, v210 row_shl:8 row_mask:0xf bank_mask:0x3
	v_mov_b32_dpp v215, v211 row_shl:8 row_mask:0xf bank_mask:0x3
	v_mov_b32_dpp v208, v204 row_shr:8 row_mask:0xf bank_mask:0xc
	v_mov_b32_dpp v209, v205 row_shr:8 row_mask:0xf bank_mask:0xc
	v_mov_b32_dpp v210, v206 row_shr:8 row_mask:0xf bank_mask:0xc
	v_mov_b32_dpp v211, v207 row_shr:8 row_mask:0xf bank_mask:0xc
	s_mov_b64 s[98:99], 0x80000
	v_lshl_add_u64 v[180:181], v[200:201], 0, s[98:99]
	s_mov_b64 s[98:99], 0x88000
	v_lshl_add_u64 v[182:183], v[200:201], 0, s[98:99]
	global_store_dwordx4 v[180:181], v[208:211], off
	global_store_dwordx4 v[182:183], v[212:215], off
	s_nop 1
	s_mov_b64 s[98:99], 0xa0000
	v_lshl_add_u64 v[202:203], v[200:201], 0, s[98:99]
	s_mov_b64 s[98:99], 0xa8000
	v_lshl_add_u64 v[178:179], v[200:201], 0, s[98:99]
	global_load_dwordx4 v[208:211], v[202:203], off
	global_load_dwordx4 v[212:215], v[178:179], off
	s_waitcnt vmcnt(12)
	v_mov_b32_e32 v204, v216
	v_mov_b32_e32 v205, v217
	v_mov_b32_e32 v206, v218
	v_mov_b32_e32 v207, v219
	v_mov_b32_dpp v216, v220 row_shr:8 row_mask:0xf bank_mask:0xc
	v_mov_b32_dpp v217, v221 row_shr:8 row_mask:0xf bank_mask:0xc
	v_mov_b32_dpp v218, v222 row_shr:8 row_mask:0xf bank_mask:0xc
	v_mov_b32_dpp v219, v223 row_shr:8 row_mask:0xf bank_mask:0xc
	v_mov_b32_dpp v220, v204 row_shl:8 row_mask:0xf bank_mask:0x3
	v_mov_b32_dpp v221, v205 row_shl:8 row_mask:0xf bank_mask:0x3
	v_mov_b32_dpp v222, v206 row_shl:8 row_mask:0xf bank_mask:0x3
	v_mov_b32_dpp v223, v207 row_shl:8 row_mask:0xf bank_mask:0x3
	v_pk_fma_f32 v[216:217], v[62:63], v[54:55], v[216:217]
	v_pk_fma_f32 v[218:219], v[64:65], v[56:57], v[218:219]
	v_pk_fma_f32 v[220:221], v[58:59], v[50:51], v[220:221]
	v_pk_fma_f32 v[222:223], v[60:61], v[52:53], v[222:223]
	v_mov_b32_e32 v204, v220
	v_mov_b32_e32 v205, v221
	v_mov_b32_e32 v206, v222
	v_mov_b32_e32 v207, v223
	v_mov_b32_dpp v220, v216 row_shl:8 row_mask:0xf bank_mask:0x3
	v_mov_b32_dpp v221, v217 row_shl:8 row_mask:0xf bank_mask:0x3
	v_mov_b32_dpp v222, v218 row_shl:8 row_mask:0xf bank_mask:0x3
	v_mov_b32_dpp v223, v219 row_shl:8 row_mask:0xf bank_mask:0x3
	v_mov_b32_dpp v216, v204 row_shr:8 row_mask:0xf bank_mask:0xc
	v_mov_b32_dpp v217, v205 row_shr:8 row_mask:0xf bank_mask:0xc
	v_mov_b32_dpp v218, v206 row_shr:8 row_mask:0xf bank_mask:0xc
	v_mov_b32_dpp v219, v207 row_shr:8 row_mask:0xf bank_mask:0xc
	global_store_dwordx4 v[180:181], v[216:219], off offset:512
	global_store_dwordx4 v[182:183], v[220:223], off offset:512
	s_nop 1
	global_load_dwordx4 v[216:219], v[202:203], off offset:512
	global_load_dwordx4 v[220:223], v[178:179], off offset:512
	s_waitcnt vmcnt(12)
	v_mov_b32_e32 v204, v224
	v_mov_b32_e32 v205, v225
	v_mov_b32_e32 v206, v226
	v_mov_b32_e32 v207, v227
	v_mov_b32_dpp v224, v228 row_shr:8 row_mask:0xf bank_mask:0xc
	v_mov_b32_dpp v225, v229 row_shr:8 row_mask:0xf bank_mask:0xc
	v_mov_b32_dpp v226, v230 row_shr:8 row_mask:0xf bank_mask:0xc
	v_mov_b32_dpp v227, v231 row_shr:8 row_mask:0xf bank_mask:0xc
	v_mov_b32_dpp v228, v204 row_shl:8 row_mask:0xf bank_mask:0x3
	v_mov_b32_dpp v229, v205 row_shl:8 row_mask:0xf bank_mask:0x3
	v_mov_b32_dpp v230, v206 row_shl:8 row_mask:0xf bank_mask:0x3
	v_mov_b32_dpp v231, v207 row_shl:8 row_mask:0xf bank_mask:0x3
	v_pk_fma_f32 v[224:225], v[46:47], v[78:79], v[224:225]
	v_pk_fma_f32 v[226:227], v[48:49], v[80:81], v[226:227]
	v_pk_fma_f32 v[228:229], v[42:43], v[74:75], v[228:229]
	v_pk_fma_f32 v[230:231], v[44:45], v[76:77], v[230:231]
	v_mov_b32_e32 v204, v228
	v_mov_b32_e32 v205, v229
	v_mov_b32_e32 v206, v230
	v_mov_b32_e32 v207, v231
	v_mov_b32_dpp v228, v224 row_shl:8 row_mask:0xf bank_mask:0x3
	v_mov_b32_dpp v229, v225 row_shl:8 row_mask:0xf bank_mask:0x3
	v_mov_b32_dpp v230, v226 row_shl:8 row_mask:0xf bank_mask:0x3
	v_mov_b32_dpp v231, v227 row_shl:8 row_mask:0xf bank_mask:0x3
	v_mov_b32_dpp v224, v204 row_shr:8 row_mask:0xf bank_mask:0xc
	v_mov_b32_dpp v225, v205 row_shr:8 row_mask:0xf bank_mask:0xc
	v_mov_b32_dpp v226, v206 row_shr:8 row_mask:0xf bank_mask:0xc
	v_mov_b32_dpp v227, v207 row_shr:8 row_mask:0xf bank_mask:0xc
	s_mov_b64 s[98:99], 0x90000
	v_lshl_add_u64 v[180:181], v[200:201], 0, s[98:99]
	s_mov_b64 s[98:99], 0x98000
	v_lshl_add_u64 v[182:183], v[200:201], 0, s[98:99]
	global_store_dwordx4 v[180:181], v[224:227], off
	global_store_dwordx4 v[182:183], v[228:231], off
	s_nop 1
	s_mov_b64 s[98:99], 0xb0000
	v_lshl_add_u64 v[202:203], v[200:201], 0, s[98:99]
	s_mov_b64 s[98:99], 0xb8000
	v_lshl_add_u64 v[178:179], v[200:201], 0, s[98:99]
	global_load_dwordx4 v[224:227], v[202:203], off
	global_load_dwordx4 v[228:231], v[178:179], off
	s_waitcnt vmcnt(12)
;     DI void operator()(const f32x4 (&acc)[2][2][4][2], const Unit& u, int wr, int wc, int fr, int fq) const {
;     ...
;         for (int ai = 0; ai < 2; ++ai)
; #pragma unroll
;             for (int m = 0; m < 4; ++m) { const size_t r = (size_t)(row0 + ai * 128 + m * 16);
; #pragma unroll
;                 for (int bj = 0; bj < 2; ++bj) { const size_t off = r * 1024 + col0 + bj * 128;
;                     f32x4 v0 = *(const f32x4*)(base + off), v1 = *(const f32x4*)(base + off + 4);
;                     v0 += g[bj][0] * acc[ai][bj][m][0]; v1 += g[bj][1] * acc[ai][bj][m][1];
;                     *(f32x4*)(out + off) = v0; *(f32x4*)(out + off + 4) = v1; } }
	v_mov_b32_e32 v204, v232
	v_mov_b32_e32 v205, v233
	v_mov_b32_e32 v206, v234
	v_mov_b32_e32 v207, v235
	v_mov_b32_dpp v232, v236 row_shr:8 row_mask:0xf bank_mask:0xc
	v_mov_b32_dpp v233, v237 row_shr:8 row_mask:0xf bank_mask:0xc
	v_mov_b32_dpp v234, v238 row_shr:8 row_mask:0xf bank_mask:0xc
	v_mov_b32_dpp v235, v239 row_shr:8 row_mask:0xf bank_mask:0xc
	v_mov_b32_dpp v236, v204 row_shl:8 row_mask:0xf bank_mask:0x3
	v_mov_b32_dpp v237, v205 row_shl:8 row_mask:0xf bank_mask:0x3
	v_mov_b32_dpp v238, v206 row_shl:8 row_mask:0xf bank_mask:0x3
	v_mov_b32_dpp v239, v207 row_shl:8 row_mask:0xf bank_mask:0x3
	v_pk_fma_f32 v[232:233], v[38:39], v[54:55], v[232:233]
	v_pk_fma_f32 v[234:235], v[40:41], v[56:57], v[234:235]
	v_pk_fma_f32 v[236:237], v[34:35], v[50:51], v[236:237]
	v_pk_fma_f32 v[238:239], v[36:37], v[52:53], v[238:239]
	v_mov_b32_e32 v204, v236
	v_mov_b32_e32 v205, v237
	v_mov_b32_e32 v206, v238
	v_mov_b32_e32 v207, v239
	v_mov_b32_dpp v236, v232 row_shl:8 row_mask:0xf bank_mask:0x3
	v_mov_b32_dpp v237, v233 row_shl:8 row_mask:0xf bank_mask:0x3
	v_mov_b32_dpp v238, v234 row_shl:8 row_mask:0xf bank_mask:0x3
	v_mov_b32_dpp v239, v235 row_shl:8 row_mask:0xf bank_mask:0x3
	v_mov_b32_dpp v232, v204 row_shr:8 row_mask:0xf bank_mask:0xc
	v_mov_b32_dpp v233, v205 row_shr:8 row_mask:0xf bank_mask:0xc
	v_mov_b32_dpp v234, v206 row_shr:8 row_mask:0xf bank_mask:0xc
	v_mov_b32_dpp v235, v207 row_shr:8 row_mask:0xf bank_mask:0xc
	global_store_dwordx4 v[180:181], v[232:235], off offset:512
	global_store_dwordx4 v[182:183], v[236:239], off offset:512
	s_nop 1
	global_load_dwordx4 v[232:235], v[202:203], off offset:512
	global_load_dwordx4 v[236:239], v[178:179], off offset:512
	s_waitcnt vmcnt(12)
	v_mov_b32_e32 v204, v208
	v_mov_b32_e32 v205, v209
	v_mov_b32_e32 v206, v210
	v_mov_b32_e32 v207, v211
	v_mov_b32_dpp v208, v212 row_shr:8 row_mask:0xf bank_mask:0xc
	v_mov_b32_dpp v209, v213 row_shr:8 row_mask:0xf bank_mask:0xc
	v_mov_b32_dpp v210, v214 row_shr:8 row_mask:0xf bank_mask:0xc
	v_mov_b32_dpp v211, v215 row_shr:8 row_mask:0xf bank_mask:0xc
	v_mov_b32_dpp v212, v204 row_shl:8 row_mask:0xf bank_mask:0x3
	v_mov_b32_dpp v213, v205 row_shl:8 row_mask:0xf bank_mask:0x3
	v_mov_b32_dpp v214, v206 row_shl:8 row_mask:0xf bank_mask:0x3
	v_mov_b32_dpp v215, v207 row_shl:8 row_mask:0xf bank_mask:0x3
	v_pk_fma_f32 v[208:209], v[30:31], v[78:79], v[208:209]
	v_pk_fma_f32 v[210:211], v[32:33], v[80:81], v[210:211]
	v_pk_fma_f32 v[212:213], v[26:27], v[74:75], v[212:213]
	v_pk_fma_f32 v[214:215], v[28:29], v[76:77], v[214:215]
	v_mov_b32_e32 v204, v212
	v_mov_b32_e32 v205, v213
	v_mov_b32_e32 v206, v214
	v_mov_b32_e32 v207, v215
	v_mov_b32_dpp v212, v208 row_shl:8 row_mask:0xf bank_mask:0x3
	v_mov_b32_dpp v213, v209 row_shl:8 row_mask:0xf bank_mask:0x3
	v_mov_b32_dpp v214, v210 row_shl:8 row_mask:0xf bank_mask:0x3
	v_mov_b32_dpp v215, v211 row_shl:8 row_mask:0xf bank_mask:0x3
	v_mov_b32_dpp v208, v204 row_shr:8 row_mask:0xf bank_mask:0xc
	v_mov_b32_dpp v209, v205 row_shr:8 row_mask:0xf bank_mask:0xc
	v_mov_b32_dpp v210, v206 row_shr:8 row_mask:0xf bank_mask:0xc
	v_mov_b32_dpp v211, v207 row_shr:8 row_mask:0xf bank_mask:0xc
	s_mov_b64 s[98:99], 0xa0000
	v_lshl_add_u64 v[180:181], v[200:201], 0, s[98:99]
	s_mov_b64 s[98:99], 0xa8000
	v_lshl_add_u64 v[182:183], v[200:201], 0, s[98:99]
	global_store_dwordx4 v[180:181], v[208:211], off
	global_store_dwordx4 v[182:183], v[212:215], off
	s_waitcnt vmcnt(10)
	v_mov_b32_e32 v204, v216
	v_mov_b32_e32 v205, v217
	v_mov_b32_e32 v206, v218
	v_mov_b32_e32 v207, v219
	v_mov_b32_dpp v216, v220 row_shr:8 row_mask:0xf bank_mask:0xc
	v_mov_b32_dpp v217, v221 row_shr:8 row_mask:0xf bank_mask:0xc
	v_mov_b32_dpp v218, v222 row_shr:8 row_mask:0xf bank_mask:0xc
	v_mov_b32_dpp v219, v223 row_shr:8 row_mask:0xf bank_mask:0xc
	v_mov_b32_dpp v220, v204 row_shl:8 row_mask:0xf bank_mask:0x3
	v_mov_b32_dpp v221, v205 row_shl:8 row_mask:0xf bank_mask:0x3
	v_mov_b32_dpp v222, v206 row_shl:8 row_mask:0xf bank_mask:0x3
	v_mov_b32_dpp v223, v207 row_shl:8 row_mask:0xf bank_mask:0x3
	v_pk_fma_f32 v[216:217], v[22:23], v[54:55], v[216:217]
	v_pk_fma_f32 v[218:219], v[24:25], v[56:57], v[218:219]
	v_pk_fma_f32 v[220:221], v[18:19], v[50:51], v[220:221]
	v_pk_fma_f32 v[222:223], v[20:21], v[52:53], v[222:223]
	v_mov_b32_e32 v204, v220
	v_mov_b32_e32 v205, v221
	v_mov_b32_e32 v206, v222
	v_mov_b32_e32 v207, v223
	v_mov_b32_dpp v220, v216 row_shl:8 row_mask:0xf bank_mask:0x3
	v_mov_b32_dpp v221, v217 row_shl:8 row_mask:0xf bank_mask:0x3
	v_mov_b32_dpp v222, v218 row_shl:8 row_mask:0xf bank_mask:0x3
	v_mov_b32_dpp v223, v219 row_shl:8 row_mask:0xf bank_mask:0x3
	v_mov_b32_dpp v216, v204 row_shr:8 row_mask:0xf bank_mask:0xc
	v_mov_b32_dpp v217, v205 row_shr:8 row_mask:0xf bank_mask:0xc
	v_mov_b32_dpp v218, v206 row_shr:8 row_mask:0xf bank_mask:0xc
	v_mov_b32_dpp v219, v207 row_shr:8 row_mask:0xf bank_mask:0xc
	global_store_dwordx4 v[180:181], v[216:219], off offset:512
	global_store_dwordx4 v[182:183], v[220:223], off offset:512
	s_waitcnt vmcnt(8)
; template <class Epi, class Sched, bool ALIGN_EPI = false, bool SP2 = false>
; __device__ __forceinline__ void gemm_phase(PG8_LAS unsigned char* lds, const Gemm g, const Sched& S, const Epi& E) {
;     ...
;         if constexpr (!Epi::AFTER_DRAIN) { E(acc, cur, wr, wc, fr, fq); S.done(cur); }
;         if (!has_next) break;
;     DI void operator()(const f32x4 (&acc)[2][2][4][2], const Unit& u, int wr, int wc, int fr, int fq) const {
;     ...
;         for (int ai = 0; ai < 2; ++ai)
; #pragma unroll
;             for (int m = 0; m < 4; ++m) { const size_t r = (size_t)(row0 + ai * 128 + m * 16);
; #pragma unroll
;                 for (int bj = 0; bj < 2; ++bj) { const size_t off = r * 1024 + col0 + bj * 128;
;                     f32x4 v0 = *(const f32x4*)(base + off), v1 = *(const f32x4*)(base + off + 4);
;                     v0 += g[bj][0] * acc[ai][bj][m][0]; v1 += g[bj][1] * acc[ai][bj][m][1];
;                     *(f32x4*)(out + off) = v0; *(f32x4*)(out + off + 4) = v1; } }
	v_mov_b32_e32 v204, v224
	v_mov_b32_e32 v205, v225
	v_mov_b32_e32 v206, v226
	v_mov_b32_e32 v207, v227
	v_mov_b32_dpp v224, v228 row_shr:8 row_mask:0xf bank_mask:0xc
	v_mov_b32_dpp v225, v229 row_shr:8 row_mask:0xf bank_mask:0xc
	v_mov_b32_dpp v226, v230 row_shr:8 row_mask:0xf bank_mask:0xc
	v_mov_b32_dpp v227, v231 row_shr:8 row_mask:0xf bank_mask:0xc
	v_mov_b32_dpp v228, v204 row_shl:8 row_mask:0xf bank_mask:0x3
	v_mov_b32_dpp v229, v205 row_shl:8 row_mask:0xf bank_mask:0x3
	v_mov_b32_dpp v230, v206 row_shl:8 row_mask:0xf bank_mask:0x3
	v_mov_b32_dpp v231, v207 row_shl:8 row_mask:0xf bank_mask:0x3
	v_pk_fma_f32 v[224:225], v[14:15], v[78:79], v[224:225]
	v_pk_fma_f32 v[226:227], v[16:17], v[80:81], v[226:227]
	v_pk_fma_f32 v[228:229], v[10:11], v[74:75], v[228:229]
	v_pk_fma_f32 v[230:231], v[12:13], v[76:77], v[230:231]
	v_mov_b32_e32 v204, v228
	v_mov_b32_e32 v205, v229
	v_mov_b32_e32 v206, v230
	v_mov_b32_e32 v207, v231
	v_mov_b32_dpp v228, v224 row_shl:8 row_mask:0xf bank_mask:0x3
	v_mov_b32_dpp v229, v225 row_shl:8 row_mask:0xf bank_mask:0x3
	v_mov_b32_dpp v230, v226 row_shl:8 row_mask:0xf bank_mask:0x3
	v_mov_b32_dpp v231, v227 row_shl:8 row_mask:0xf bank_mask:0x3
	v_mov_b32_dpp v224, v204 row_shr:8 row_mask:0xf bank_mask:0xc
	v_mov_b32_dpp v225, v205 row_shr:8 row_mask:0xf bank_mask:0xc
	v_mov_b32_dpp v226, v206 row_shr:8 row_mask:0xf bank_mask:0xc
	v_mov_b32_dpp v227, v207 row_shr:8 row_mask:0xf bank_mask:0xc
	s_mov_b64 s[98:99], 0xb0000
	v_lshl_add_u64 v[180:181], v[200:201], 0, s[98:99]
	s_mov_b64 s[98:99], 0xb8000
	v_lshl_add_u64 v[182:183], v[200:201], 0, s[98:99]
	global_store_dwordx4 v[180:181], v[224:227], off
	global_store_dwordx4 v[182:183], v[228:231], off
	s_waitcnt vmcnt(6)
	v_mov_b32_e32 v204, v232
	v_mov_b32_e32 v205, v233
	v_mov_b32_e32 v206, v234
	v_mov_b32_e32 v207, v235
	v_mov_b32_dpp v232, v236 row_shr:8 row_mask:0xf bank_mask:0xc
	v_mov_b32_dpp v233, v237 row_shr:8 row_mask:0xf bank_mask:0xc
	v_mov_b32_dpp v234, v238 row_shr:8 row_mask:0xf bank_mask:0xc
	v_mov_b32_dpp v235, v239 row_shr:8 row_mask:0xf bank_mask:0xc
	v_mov_b32_dpp v236, v204 row_shl:8 row_mask:0xf bank_mask:0x3
	v_mov_b32_dpp v237, v205 row_shl:8 row_mask:0xf bank_mask:0x3
	v_mov_b32_dpp v238, v206 row_shl:8 row_mask:0xf bank_mask:0x3
	v_mov_b32_dpp v239, v207 row_shl:8 row_mask:0xf bank_mask:0x3
	v_pk_fma_f32 v[232:233], v[6:7], v[54:55], v[232:233]
	v_pk_fma_f32 v[234:235], v[8:9], v[56:57], v[234:235]
	v_pk_fma_f32 v[236:237], v[2:3], v[50:51], v[236:237]
	v_pk_fma_f32 v[238:239], v[4:5], v[52:53], v[238:239]
	v_mov_b32_e32 v204, v236
	v_mov_b32_e32 v205, v237
	v_mov_b32_e32 v206, v238
	v_mov_b32_e32 v207, v239
	v_mov_b32_dpp v236, v232 row_shl:8 row_mask:0xf bank_mask:0x3
	v_mov_b32_dpp v237, v233 row_shl:8 row_mask:0xf bank_mask:0x3
	v_mov_b32_dpp v238, v234 row_shl:8 row_mask:0xf bank_mask:0x3
	v_mov_b32_dpp v239, v235 row_shl:8 row_mask:0xf bank_mask:0x3
	v_mov_b32_dpp v232, v204 row_shr:8 row_mask:0xf bank_mask:0xc
	v_mov_b32_dpp v233, v205 row_shr:8 row_mask:0xf bank_mask:0xc
	v_mov_b32_dpp v234, v206 row_shr:8 row_mask:0xf bank_mask:0xc
	v_mov_b32_dpp v235, v207 row_shr:8 row_mask:0xf bank_mask:0xc
	global_store_dwordx4 v[180:181], v[232:235], off offset:512
	global_store_dwordx4 v[182:183], v[236:239], off offset:512
	s_mov_b32 s7, 0xb0000
	s_mov_b64 s[16:17], -1
	s_andn2_b64 vcc, exec, s[0:1]
	s_cbranch_vccnz .LBB0_804
	s_andn2_b64 vcc, exec, s[2:3]
	s_cbranch_vccnz .LBB0_803
	s_barrier
	s_branch .LBB0_803
